# speedup vs baseline: 1.0281x; 1.0281x over previous
; DEV int otid() { int t = threadIdx.x; asm volatile("" : "+v"(t)); return t; }
;   const int tid = otid(), lane = tid & 63, w = __builtin_amdgcn_readfirstlane(tid >> 6), wm = w >> 1, wn = w & 1, r32 = lane & 31, hh = lane >> 5;
;   f32x16 acc[MI / 2][2][2];
; #pragma unroll
;   for (int h = 0; h < MI / 2; ++h) { acc[h][0][0] = zero16(); acc[h][0][1] = zero16(); acc[h][1][0] = zero16(); acc[h][1][1] = zero16(); }
;   const int lrow = lane >> 2, lp = (lane & 3) ^ ((lane >> 4) & 3);
;   const bf16_t* ag = uni_ptr(A + (size_t)m0 * lda + kbeg);
;   const bf16_t* bg = uni_ptr(Bt + (size_t)n0 * ldb + kbeg);
;   const unsigned voffa = ((unsigned)lrow * (unsigned)lda + (unsigned)lp * 8u) * 2u;
;   const unsigned voffb = ((unsigned)lrow * (unsigned)ldb + (unsigned)lp * 8u) * 2u;
;   const int nk = (kend - kbeg) >> 5;
;   if (!pre) {
;     asm volatile("s_waitcnt vmcnt(0)" ::: "memory");
;     g2_issue<MI>(ag, bg, lda, ldb, voffa, voffb, lds, w);
;     if (nk > 1) g2_issue<MI>(ag + 32, bg + 32, lda, ldb, voffa, voffb, lds + G2_STAGE, w);
;   }
;   const int key = (r32 >> 2) & 3;
;   const int aoff = (wm * (MI * 32) + r32) * 64;
;   const int boff = 16384 + (wn * 64 + r32) * 64;
;   const int p0 = ((0 + hh) ^ key) * 16, p1 = ((2 + hh) ^ key) * 16;
;   const unsigned lbase = (unsigned)(size_t)lds;
;   const unsigned la0 = lbase + aoff + p0, la1 = lbase + aoff + p1, lb0 = lbase + boff + p0, lb1 = lbase + boff + p1;
;   int stg = 0;
;   for (int kt = 0; kt < nk; ++kt) {
;     if (kt + 1 < nk) { if (MI == 4) asm volatile("s_waitcnt vmcnt(6)" ::: "memory"); else asm volatile("s_waitcnt vmcnt(4)" ::: "memory"); } else asm volatile("s_waitcnt vmcnt(0)" ::: "memory");
;     __builtin_amdgcn_s_barrier();
;     if (kt + 2 < nk) { int s2 = stg + 2; if (s2 >= 3) s2 -= 3; g2_issue<MI>(ag + (size_t)(kt + 2) * 32, bg + (size_t)(kt + 2) * 32, lda, ldb, voffa, voffb, lds + s2 * G2_STAGE, w); }
.LBB0_78:
	s_xor_b64 s[0:1], s[2:3], -1
	s_and_b32 s52, s53, 0xffffff80
	s_and_b32 s53, s53, 64
	s_lshl_b32 s59, s54, 12
	s_lshl_b32 s58, s55, 10
	s_lshl_b32 s57, s56, 10
	s_lshl_b32 s56, s63, 10
	s_lshl_b32 s55, s54, 11
	s_lshl_b32 s54, s64, 10
	s_add_u32 s16, s60, 0x80
	s_addc_u32 s17, s61, 0
	s_lshl_b64 s[4:5], s[4:5], 1
	s_add_u32 s60, s16, s4
	s_addc_u32 s61, s17, s5
	s_lshl_b64 s[8:9], s[8:9], 1
	s_add_u32 s63, s16, s8
	s_addc_u32 s64, s17, s9
	s_add_u32 s18, s18, 0x80
	s_addc_u32 s19, s19, 0
	s_lshl_b64 s[10:11], s[10:11], 1
	s_add_u32 s74, s18, s10
	s_addc_u32 s75, s19, s11
	s_lshl_b64 s[12:13], s[12:13], 1
	s_add_u32 s76, s18, s12
	v_and_b32_e32 v3, 63, v2
	s_addc_u32 s77, s19, s13
	s_lshl_b64 s[14:15], s[14:15], 1
	v_and_b32_e32 v130, 31, v2
	v_lshrrev_b32_e32 v133, 5, v3
	v_lshrrev_b32_e32 v3, 2, v2
	v_bfe_u32 v2, v2, 2, 2
	s_add_u32 s78, s18, s14
	v_or_b32_e32 v4, s52, v130
	v_bitop3_b32 v2, v133, v2, 2 bitop3:0x36
	s_addc_u32 s79, s19, s15
	s_lshl_b64 s[16:17], s[6:7], 1
	v_lshlrev_b32_e32 v141, 6, v4
	v_or_b32_e32 v4, s53, v130
	v_bitop3_b32 v3, v133, v3, 3 bitop3:0x78
	v_lshlrev_b32_e32 v138, 4, v2
	s_add_u32 s7, s18, s16
	v_mov_b32_e32 v2, 0
	v_lshl_or_b32 v143, v4, 6, v209
	v_lshlrev_b32_e32 v145, 4, v3
	s_addc_u32 s80, s19, s17
	s_mov_b32 s6, 0
	s_mov_b64 s[18:19], 0
	v_mov_b32_e32 v3, v2
	v_mov_b32_e32 v4, v2
	v_mov_b32_e32 v5, v2
	v_mov_b32_e32 v6, v2
	v_mov_b32_e32 v7, v2
	v_mov_b32_e32 v8, v2
	v_mov_b32_e32 v9, v2
	v_mov_b32_e32 v10, v2
	v_mov_b32_e32 v11, v2
	v_mov_b32_e32 v12, v2
	v_mov_b32_e32 v13, v2
	v_mov_b32_e32 v14, v2
	v_mov_b32_e32 v15, v2
	v_mov_b32_e32 v16, v2
	v_mov_b32_e32 v17, v2
	v_mov_b32_e32 v18, v2
	v_mov_b32_e32 v19, v2
	v_mov_b32_e32 v20, v2
	v_mov_b32_e32 v21, v2
	v_mov_b32_e32 v22, v2
	v_mov_b32_e32 v23, v2
	v_mov_b32_e32 v24, v2
	v_mov_b32_e32 v25, v2
	v_mov_b32_e32 v26, v2
	v_mov_b32_e32 v27, v2
	v_mov_b32_e32 v28, v2
	v_mov_b32_e32 v29, v2
	v_mov_b32_e32 v30, v2
	v_mov_b32_e32 v31, v2
	v_mov_b32_e32 v32, v2
	v_mov_b32_e32 v33, v2
	v_mov_b32_e32 v34, v2
	v_mov_b32_e32 v35, v2
	v_mov_b32_e32 v36, v2
	v_mov_b32_e32 v37, v2
	v_mov_b32_e32 v38, v2
	v_mov_b32_e32 v39, v2
	v_mov_b32_e32 v40, v2
	v_mov_b32_e32 v41, v2
	v_mov_b32_e32 v42, v2
	v_mov_b32_e32 v43, v2
	v_mov_b32_e32 v44, v2
	v_mov_b32_e32 v45, v2
	v_mov_b32_e32 v46, v2
	v_mov_b32_e32 v47, v2
	v_mov_b32_e32 v48, v2
	v_mov_b32_e32 v49, v2
	v_mov_b32_e32 v50, v2
	v_mov_b32_e32 v51, v2
	v_mov_b32_e32 v52, v2
	v_mov_b32_e32 v53, v2
	v_mov_b32_e32 v54, v2
	v_mov_b32_e32 v55, v2
	v_mov_b32_e32 v56, v2
	v_mov_b32_e32 v57, v2
	v_mov_b32_e32 v58, v2
	v_mov_b32_e32 v59, v2
	v_mov_b32_e32 v60, v2
	v_mov_b32_e32 v61, v2
	v_mov_b32_e32 v62, v2
	v_mov_b32_e32 v63, v2
	v_mov_b32_e32 v64, v2
	v_mov_b32_e32 v65, v2
	v_mov_b32_e32 v66, v2
	v_mov_b32_e32 v67, v2
	v_mov_b32_e32 v68, v2
	v_mov_b32_e32 v69, v2
	v_mov_b32_e32 v70, v2
	v_mov_b32_e32 v71, v2
	v_mov_b32_e32 v72, v2
	v_mov_b32_e32 v73, v2
	v_mov_b32_e32 v74, v2
	v_mov_b32_e32 v75, v2
	v_mov_b32_e32 v76, v2
	v_mov_b32_e32 v77, v2
	v_mov_b32_e32 v78, v2
	v_mov_b32_e32 v79, v2
	v_mov_b32_e32 v80, v2
	v_mov_b32_e32 v81, v2
	v_mov_b32_e32 v82, v2
	v_mov_b32_e32 v83, v2
	v_mov_b32_e32 v84, v2
	v_mov_b32_e32 v85, v2
	v_mov_b32_e32 v86, v2
	v_mov_b32_e32 v87, v2
	v_mov_b32_e32 v88, v2
	v_mov_b32_e32 v89, v2
	v_mov_b32_e32 v90, v2
	v_mov_b32_e32 v91, v2
	v_mov_b32_e32 v92, v2
	v_mov_b32_e32 v93, v2
	v_mov_b32_e32 v94, v2
	v_mov_b32_e32 v95, v2
	v_mov_b32_e32 v96, v2
	v_mov_b32_e32 v97, v2
	v_mov_b32_e32 v98, v2
	v_mov_b32_e32 v99, v2
	v_mov_b32_e32 v100, v2
	v_mov_b32_e32 v101, v2
	v_mov_b32_e32 v102, v2
	v_mov_b32_e32 v103, v2
	v_mov_b32_e32 v104, v2
	v_mov_b32_e32 v105, v2
	v_mov_b32_e32 v106, v2
	v_mov_b32_e32 v107, v2
	v_mov_b32_e32 v108, v2
	v_mov_b32_e32 v109, v2
	v_mov_b32_e32 v110, v2
	v_mov_b32_e32 v111, v2
	v_mov_b32_e32 v112, v2
	v_mov_b32_e32 v113, v2
	v_mov_b32_e32 v114, v2
	v_mov_b32_e32 v115, v2
	v_mov_b32_e32 v116, v2
	v_mov_b32_e32 v117, v2
	v_mov_b32_e32 v118, v2
	v_mov_b32_e32 v119, v2
	v_mov_b32_e32 v120, v2
	v_mov_b32_e32 v121, v2
	v_mov_b32_e32 v122, v2
	v_mov_b32_e32 v123, v2
	v_mov_b32_e32 v124, v2
	v_mov_b32_e32 v125, v2
	v_mov_b32_e32 v126, v2
	v_mov_b32_e32 v127, v2
	v_mov_b32_e32 v128, v2
	v_mov_b32_e32 v129, v2
	v_lshlrev_b32_e32 v191, 4, v200
.LBB0_79:
	s_cmp_gt_i32 s6, 0
	s_cselect_b32 s81, -1, 2
	s_add_i32 s81, s81, s6
	s_mulk_i32 s81, 0x6000
	s_add_u32 s82, s7, s18
	s_addc_u32 s83, s80, s19
	s_add_i32 s84, s59, s81
	s_cmp_eq_u32 s18, 0
	s_cbranch_scc1 .Lhyb_first_down
	s_waitcnt vmcnt(0)
	s_barrier
	s_add_i32 s98, s6, 1
	s_cmp_lg_u32 s6, 2
	s_cselect_b32 s98, s98, 0
	s_mul_i32 s98, s98, 0x6000
	s_add_i32 s99, s59, s98
	v_add_u32_e32 v238, s99, v191
	ds_write_b128 v238, v[214:217]
	s_add_i32 s99, s58, s98
	v_add_u32_e32 v190, s99, v191
	ds_write_b128 v190, v[218:221]
	s_add_i32 s99, s57, s98
	v_add_u32_e32 v238, s99, v191
	ds_write_b128 v238, v[222:225]
	s_add_i32 s99, s56, s98
	v_add_u32_e32 v190, s99, v191
	ds_write_b128 v190, v[226:229]
	s_add_i32 s99, s55, s98
	s_addk_i32 s99, 0x4000
	v_add_u32_e32 v238, s99, v191
	ds_write_b128 v238, v[230:233]
	s_add_i32 s99, s54, s98
	s_addk_i32 s99, 0x4000
	v_add_u32_e32 v190, s99, v191
	ds_write_b128 v190, v[234:237]
	s_branch .Lhyb_issue_down
.Lhyb_first_down:
	s_waitcnt vmcnt(6)
	s_barrier
; template <int MI>
; DEV void g2_issue(const bf16_t* __restrict__ abase, const bf16_t* __restrict__ bbase, size_t lda, size_t ldb, unsigned voffa, unsigned voffb,
;                   char* st, int w) {
;   const unsigned base = (unsigned)(size_t)st;
; #pragma unroll
;   for (int c = 0; c < MI; ++c) {
;     const int j = w * MI + c;
;     dma16s(abase + (size_t)(16 * j) * lda, voffa, __builtin_amdgcn_readfirstlane(base + j * 1024));
;   }
; #pragma unroll
;   for (int c = 0; c < 2; ++c) {
;     const int j = w * 2 + c;
;     dma16s(bbase + (size_t)(16 * j) * ldb, voffb, __builtin_amdgcn_readfirstlane(base + 16384 + j * 1024));
;   }
; }
.Lhyb_issue_down:
	s_cmpk_eq_i32 s18, 0x2b80
	s_cbranch_scc1 .Lhyb_comp_down
	s_mov_b32 m0, s84
	s_nop 0
	global_load_lds_dwordx4 v1, s[82:83]
	global_load_dwordx4 v[214:217], v1, s[82:83] offset:64
	s_add_u32 s82, s78, s18
	s_addc_u32 s83, s79, s19
	s_add_i32 s84, s58, s81
	s_mov_b32 m0, s84
	s_nop 0
	global_load_lds_dwordx4 v1, s[82:83]
	global_load_dwordx4 v[218:221], v1, s[82:83] offset:64
	s_add_u32 s82, s76, s18
	s_addc_u32 s83, s77, s19
	s_add_i32 s84, s57, s81
	s_mov_b32 m0, s84
	s_nop 0
	global_load_lds_dwordx4 v1, s[82:83]
	global_load_dwordx4 v[222:225], v1, s[82:83] offset:64
	s_add_u32 s82, s74, s18
	s_addc_u32 s83, s75, s19
	s_add_i32 s84, s56, s81
	s_addk_i32 s81, 0x4000
	s_mov_b32 m0, s84
	s_nop 0
	global_load_lds_dwordx4 v1, s[82:83]
	global_load_dwordx4 v[226:229], v1, s[82:83] offset:64
	s_add_u32 s82, s63, s18
	s_addc_u32 s83, s64, s19
	s_add_i32 s84, s81, s55
	s_mov_b32 m0, s84
	s_nop 0
	global_load_lds_dwordx4 v1, s[82:83]
	global_load_dwordx4 v[230:233], v1, s[82:83] offset:64
	s_add_u32 s82, s60, s18
	s_addc_u32 s83, s61, s19
	s_add_i32 s81, s81, s54
	s_mov_b32 m0, s81
	s_nop 0
	global_load_lds_dwordx4 v1, s[82:83]
	global_load_dwordx4 v[234:237], v1, s[82:83] offset:64
;     ...
;     const unsigned so = (unsigned)(stg * G2_STAGE);
;     __builtin_amdgcn_s_setprio(1);
; #pragma unroll
;     for (int ks = 0; ks < 2; ++ks) {
;       const unsigned aa = (ks ? la1 : la0) + so, bb = (ks ? lb1 : lb0) + so;
;       bf16x8 fb0, fb1, fa0, fa1, fa2, fa3;
;       asm volatile("ds_read_b128 %0, %1" : "=v"(fb0) : "v"(bb));
;       asm volatile("ds_read_b128 %0, %1 offset:2048" : "=v"(fb1) : "v"(bb));
;       asm volatile("ds_read_b128 %0, %1" : "=v"(fa0) : "v"(aa));
;       asm volatile("ds_read_b128 %0, %1 offset:2048" : "=v"(fa1) : "v"(aa));
;       if constexpr (MI == 4) {
;         asm volatile("ds_read_b128 %0, %1 offset:4096" : "=v"(fa2) : "v"(aa));
;         asm volatile("ds_read_b128 %0, %1 offset:6144" : "=v"(fa3) : "v"(aa));
;         __builtin_amdgcn_sched_barrier(0);
;         asm volatile("s_waitcnt lgkmcnt(3)" : "+v"(fb0), "+v"(fb1), "+v"(fa0));
;         acc[0][0][0] = mfma(fa0, fb0, acc[0][0][0]); acc[0][0][1] = mfma(fa0, fb1, acc[0][0][1]); __builtin_amdgcn_sched_barrier(0);
;         asm volatile("s_waitcnt lgkmcnt(2)" : "+v"(fa1));
;         acc[0][1][0] = mfma(fa1, fb0, acc[0][1][0]); acc[0][1][1] = mfma(fa1, fb1, acc[0][1][1]); __builtin_amdgcn_sched_barrier(0);
;         asm volatile("s_waitcnt lgkmcnt(1)" : "+v"(fa2));
;         acc[MI / 2 - 1][0][0] = mfma(fa2, fb0, acc[MI / 2 - 1][0][0]); acc[MI / 2 - 1][0][1] = mfma(fa2, fb1, acc[MI / 2 - 1][0][1]); __builtin_amdgcn_sched_barrier(0);
;         asm volatile("s_waitcnt lgkmcnt(0)" : "+v"(fa3));
;         acc[MI / 2 - 1][1][0] = mfma(fa3, fb0, acc[MI / 2 - 1][1][0]); acc[MI / 2 - 1][1][1] = mfma(fa3, fb1, acc[MI / 2 - 1][1][1]); __builtin_amdgcn_sched_barrier(0);
;       } else {
;         __builtin_amdgcn_sched_barrier(0);
;         asm volatile("s_waitcnt lgkmcnt(1)" : "+v"(fb0), "+v"(fb1), "+v"(fa0));
;         acc[0][0][0] = mfma(fa0, fb0, acc[0][0][0]); acc[0][0][1] = mfma(fa0, fb1, acc[0][0][1]); __builtin_amdgcn_sched_barrier(0);
;         asm volatile("s_waitcnt lgkmcnt(0)" : "+v"(fa1));
;         acc[0][1][0] = mfma(fa1, fb0, acc[0][1][0]); acc[0][1][1] = mfma(fa1, fb1, acc[0][1][1]); __builtin_amdgcn_sched_barrier(0);
;       }
;     }
;     __builtin_amdgcn_s_setprio(0);
;     stg = stg == 2 ? 0 : stg + 1;
;   }
;   __syncthreads();
;   if (has_next) {
;     const bf16_t* agn = uni_ptr(A + (size_t)m0n * lda + kbeg);
.Lhyb_comp_down:
	s_mul_i32 s81, s6, 0x6000
	s_setprio 1
	v_add_u32_e32 v147, s81, v141
	v_add_u32_e32 v149, s81, v143
	v_add_u32_e32 v172, v147, v145
	v_add_u32_e32 v156, v149, v145
	ds_read_b128 v[152:155], v156
	ds_read_b128 v[156:159], v156 offset:2048
	ds_read_b128 v[160:163], v172
	ds_read_b128 v[164:167], v172 offset:2048
	ds_read_b128 v[168:171], v172 offset:4096
	ds_read_b128 v[172:175], v172 offset:6144
	s_nop 0
	s_waitcnt lgkmcnt(3)
	s_nop 0
	v_mfma_f32_32x32x16_bf16 v[114:129], v[160:163], v[152:155], v[114:129]
	v_mfma_f32_32x32x16_bf16 v[98:113], v[160:163], v[156:159], v[98:113]
	s_waitcnt lgkmcnt(2)
	s_nop 0
	v_mfma_f32_32x32x16_bf16 v[82:97], v[164:167], v[152:155], v[82:97]
	v_mfma_f32_32x32x16_bf16 v[66:81], v[164:167], v[156:159], v[66:81]
	s_waitcnt lgkmcnt(1)
	s_nop 0
	v_mfma_f32_32x32x16_bf16 v[50:65], v[168:171], v[152:155], v[50:65]
	v_mfma_f32_32x32x16_bf16 v[34:49], v[168:171], v[156:159], v[34:49]
	s_waitcnt lgkmcnt(0)
	s_nop 0
	v_mfma_f32_32x32x16_bf16 v[18:33], v[172:175], v[152:155], v[18:33]
	v_mfma_f32_32x32x16_bf16 v[2:17], v[172:175], v[156:159], v[2:17]
	v_add_u32_e32 v147, v147, v138
	v_add_u32_e32 v149, v149, v138
	ds_read_b128 v[152:155], v149
	ds_read_b128 v[156:159], v149 offset:2048
	ds_read_b128 v[160:163], v147
	ds_read_b128 v[164:167], v147 offset:2048
	ds_read_b128 v[168:171], v147 offset:4096
	ds_read_b128 v[172:175], v147 offset:6144
	s_nop 0
	s_waitcnt lgkmcnt(3)
	s_nop 0
	v_mfma_f32_32x32x16_bf16 v[114:129], v[160:163], v[152:155], v[114:129]
	v_mfma_f32_32x32x16_bf16 v[98:113], v[160:163], v[156:159], v[98:113]
	s_waitcnt lgkmcnt(2)
	s_nop 0
	v_mfma_f32_32x32x16_bf16 v[82:97], v[164:167], v[152:155], v[82:97]
	v_mfma_f32_32x32x16_bf16 v[66:81], v[164:167], v[156:159], v[66:81]
	s_waitcnt lgkmcnt(1)
	s_nop 0
	v_mfma_f32_32x32x16_bf16 v[50:65], v[168:171], v[152:155], v[50:65]
	v_mfma_f32_32x32x16_bf16 v[34:49], v[168:171], v[156:159], v[34:49]
	s_waitcnt lgkmcnt(0)
	s_nop 0
	v_mfma_f32_32x32x16_bf16 v[18:33], v[172:175], v[152:155], v[18:33]
	v_mfma_f32_32x32x16_bf16 v[2:17], v[172:175], v[156:159], v[2:17]
	s_setprio 0
	s_add_i32 s98, s6, 1
	s_cmp_lg_u32 s6, 2
	s_cselect_b32 s6, s98, 0
	s_waitcnt vmcnt(12)
	s_barrier
	s_mul_i32 s81, s6, 0x6000
	s_setprio 1
	v_add_u32_e32 v147, s81, v141
	v_add_u32_e32 v149, s81, v143
	v_add_u32_e32 v172, v147, v145
	v_add_u32_e32 v156, v149, v145
	ds_read_b128 v[152:155], v156
	ds_read_b128 v[156:159], v156 offset:2048
	ds_read_b128 v[160:163], v172
	ds_read_b128 v[164:167], v172 offset:2048
	ds_read_b128 v[168:171], v172 offset:4096
	ds_read_b128 v[172:175], v172 offset:6144
	s_nop 0
	s_waitcnt lgkmcnt(3)
	s_nop 0
	v_mfma_f32_32x32x16_bf16 v[114:129], v[160:163], v[152:155], v[114:129]
	v_mfma_f32_32x32x16_bf16 v[98:113], v[160:163], v[156:159], v[98:113]
	s_waitcnt lgkmcnt(2)
	s_nop 0
	v_mfma_f32_32x32x16_bf16 v[82:97], v[164:167], v[152:155], v[82:97]
	v_mfma_f32_32x32x16_bf16 v[66:81], v[164:167], v[156:159], v[66:81]
	s_waitcnt lgkmcnt(1)
	s_nop 0
	v_mfma_f32_32x32x16_bf16 v[50:65], v[168:171], v[152:155], v[50:65]
	v_mfma_f32_32x32x16_bf16 v[34:49], v[168:171], v[156:159], v[34:49]
	s_waitcnt lgkmcnt(0)
	s_nop 0
	v_mfma_f32_32x32x16_bf16 v[18:33], v[172:175], v[152:155], v[18:33]
	v_mfma_f32_32x32x16_bf16 v[2:17], v[172:175], v[156:159], v[2:17]
	v_add_u32_e32 v147, v147, v138
	v_add_u32_e32 v149, v149, v138
	ds_read_b128 v[152:155], v149
	ds_read_b128 v[156:159], v149 offset:2048
	ds_read_b128 v[160:163], v147
	ds_read_b128 v[164:167], v147 offset:2048
	ds_read_b128 v[168:171], v147 offset:4096
	ds_read_b128 v[172:175], v147 offset:6144
	s_nop 0
	s_waitcnt lgkmcnt(3)
	s_nop 0
	v_mfma_f32_32x32x16_bf16 v[114:129], v[160:163], v[152:155], v[114:129]
	v_mfma_f32_32x32x16_bf16 v[98:113], v[160:163], v[156:159], v[98:113]
	s_waitcnt lgkmcnt(2)
	s_nop 0
	v_mfma_f32_32x32x16_bf16 v[82:97], v[164:167], v[152:155], v[82:97]
	v_mfma_f32_32x32x16_bf16 v[66:81], v[164:167], v[156:159], v[66:81]
	s_waitcnt lgkmcnt(1)
	s_nop 0
	v_mfma_f32_32x32x16_bf16 v[50:65], v[168:171], v[152:155], v[50:65]
	v_mfma_f32_32x32x16_bf16 v[34:49], v[168:171], v[156:159], v[34:49]
	s_waitcnt lgkmcnt(0)
	s_nop 0
	v_mfma_f32_32x32x16_bf16 v[18:33], v[172:175], v[152:155], v[18:33]
	v_mfma_f32_32x32x16_bf16 v[2:17], v[172:175], v[156:159], v[2:17]
	s_add_i32 s98, s6, 1
	s_cmp_lg_u32 s6, 2
	s_cselect_b32 s6, s98, 0
	s_add_u32 s18, s18, 0x80
	s_addc_u32 s19, s19, 0
	s_cmpk_eq_i32 s18, 0x2c00
	s_cbranch_scc0 .LBB0_79
	s_setprio 0
	s_and_b64 vcc, exec, s[2:3]
	s_waitcnt lgkmcnt(0)
	s_barrier
	s_cbranch_vccz .LBB0_67
	s_lshl_b32 s2, s21, 8
	s_lshl_b32 s3, s22, 7
	s_mul_i32 s6, s21, 0x2c0000
	s_mul_hi_i32 s2, s2, 0x2c00
	s_add_u32 s18, s23, s6
	s_addc_u32 s19, s24, s2
	s_mul_i32 s2, s22, 0x160000
	s_mul_hi_i32 s3, s3, 0x2c00
	s_add_u32 s60, s25, s2
	s_addc_u32 s61, s26, s3
	s_add_u32 s2, s18, s16
	s_addc_u32 s3, s19, s17
	s_add_u32 s6, s18, s14
	s_addc_u32 s7, s19, s15
	s_add_u32 s12, s18, s12
	s_addc_u32 s13, s19, s13
	s_add_u32 s10, s18, s10
	s_mov_b32 m0, s59
	s_nop 0
	global_load_lds_dwordx4 v1, s[2:3]
	s_addc_u32 s11, s19, s11
	s_mov_b32 m0, s58
	s_nop 0
	global_load_lds_dwordx4 v1, s[6:7]
	s_add_u32 s8, s60, s8
	s_mov_b32 m0, s57
	s_nop 0
	global_load_lds_dwordx4 v1, s[12:13]
	s_addc_u32 s9, s61, s9
	s_add_i32 s14, s55, 0x4000
	s_mov_b32 m0, s56
	s_nop 0
	global_load_lds_dwordx4 v1, s[10:11]
	s_add_u32 s4, s60, s4
	s_mov_b32 m0, s14
	s_nop 0
	global_load_lds_dwordx4 v1, s[8:9]
	s_addc_u32 s5, s61, s5
	s_add_i32 s14, s54, 0x4000
	s_add_u32 s2, s2, 64
	s_mov_b32 m0, s14
	s_nop 0
	global_load_lds_dwordx4 v1, s[4:5]
	s_addc_u32 s3, s3, 0
	s_add_i32 s14, s59, 0x6000
	s_mov_b32 m0, s14
	s_nop 0
	global_load_lds_dwordx4 v1, s[2:3]
	s_add_u32 s2, s6, 64
	s_addc_u32 s3, s7, 0
	s_add_i32 s6, s58, 0x6000
	s_mov_b32 m0, s6
	s_nop 0
	global_load_lds_dwordx4 v1, s[2:3]
	s_add_u32 s2, s12, 64
	s_addc_u32 s3, s13, 0
	s_add_i32 s6, s57, 0x6000
	s_mov_b32 m0, s6
	s_nop 0
	global_load_lds_dwordx4 v1, s[2:3]
	s_add_u32 s2, s10, 64
	s_addc_u32 s3, s11, 0
	s_add_i32 s6, s56, 0x6000
	s_mov_b32 m0, s6
	s_nop 0
	global_load_lds_dwordx4 v1, s[2:3]
	s_add_u32 s2, s8, 64
	s_addc_u32 s3, s9, 0
	s_add_i32 s55, s55, 0xa000
	s_mov_b32 m0, s55
	s_nop 0
	global_load_lds_dwordx4 v1, s[2:3]
	s_add_u32 s2, s4, 64
	s_addc_u32 s3, s5, 0
	s_add_i32 s54, s54, 0xa000
	s_mov_b32 m0, s54
	s_nop 0
	global_load_lds_dwordx4 v1, s[2:3]
	s_branch .LBB0_67

; DEV int otid() { int t = threadIdx.x; asm volatile("" : "+v"(t)); return t; }
;   const int tid = otid(), lane = tid & 63, w = __builtin_amdgcn_readfirstlane(tid >> 6), wm = w >> 1, wn = w & 1, r32 = lane & 31, hh = lane >> 5;
;   f32x16 acc[MI / 2][2][2];
; #pragma unroll
;   for (int h = 0; h < MI / 2; ++h) { acc[h][0][0] = zero16(); acc[h][0][1] = zero16(); acc[h][1][0] = zero16(); acc[h][1][1] = zero16(); }
;   const int lrow = lane >> 2, lp = (lane & 3) ^ ((lane >> 4) & 3);
;   const bf16_t* ag = uni_ptr(A + (size_t)m0 * lda + kbeg);
;   const bf16_t* bg = uni_ptr(Bt + (size_t)n0 * ldb + kbeg);
;   const unsigned voffa = ((unsigned)lrow * (unsigned)lda + (unsigned)lp * 8u) * 2u;
;   const unsigned voffb = ((unsigned)lrow * (unsigned)ldb + (unsigned)lp * 8u) * 2u;
;   const int nk = (kend - kbeg) >> 5;
;   if (!pre) {
;     asm volatile("s_waitcnt vmcnt(0)" ::: "memory");
;     g2_issue<MI>(ag, bg, lda, ldb, voffa, voffb, lds, w);
;     if (nk > 1) g2_issue<MI>(ag + 32, bg + 32, lda, ldb, voffa, voffb, lds + G2_STAGE, w);
;   }
;   const int key = (r32 >> 2) & 3;
;   const int aoff = (wm * (MI * 32) + r32) * 64;
;   const int boff = 16384 + (wn * 64 + r32) * 64;
;   const int p0 = ((0 + hh) ^ key) * 16, p1 = ((2 + hh) ^ key) * 16;
;   const unsigned lbase = (unsigned)(size_t)lds;
;   const unsigned la0 = lbase + aoff + p0, la1 = lbase + aoff + p1, lb0 = lbase + boff + p0, lb1 = lbase + boff + p1;
;   int stg = 0;
.LBB0_117:
	s_and_b32 s3, s55, 0xffffff80
	s_and_b32 s5, s55, 64
	s_lshl_b32 s59, s54, 12
	s_lshl_b32 s58, s56, 10
	s_lshl_b32 s57, s57, 10
	s_lshl_b32 s56, s63, 10
	s_lshl_b32 s55, s54, 11
	s_lshl_b32 s54, s64, 10
	s_add_u32 s20, s60, 0x80
	s_addc_u32 s21, s61, 0
	s_lshl_b64 s[10:11], s[10:11], 1
	s_add_u32 s60, s20, s10
	s_addc_u32 s61, s21, s11
	s_lshl_b64 s[12:13], s[12:13], 1
	s_add_u32 s63, s20, s12
	s_addc_u32 s64, s21, s13
	s_add_u32 s22, s22, 0x80
	s_addc_u32 s23, s23, 0
	s_lshl_b64 s[14:15], s[14:15], 1
	s_add_u32 s74, s22, s14
	s_addc_u32 s75, s23, s15
	s_lshl_b64 s[16:17], s[16:17], 1
	s_add_u32 s76, s22, s16
	v_and_b32_e32 v3, 63, v2
	v_and_b32_e32 v130, 31, v2
	s_addc_u32 s77, s23, s17
	s_lshl_b64 s[18:19], s[18:19], 1
	v_lshrrev_b32_e32 v133, 5, v3
	v_lshrrev_b32_e32 v3, 2, v2
	v_bfe_u32 v2, v2, 2, 2
	v_or_b32_e32 v4, s3, v130
	s_add_u32 s78, s22, s18
	v_lshlrev_b32_e32 v138, 6, v4
	v_or_b32_e32 v4, s5, v130
	v_bitop3_b32 v2, v133, v2, 2 bitop3:0x36
	s_addc_u32 s79, s23, s19
	s_lshl_b64 s[20:21], s[6:7], 1
	v_lshlrev_b32_e32 v147, 6, v4
	v_bitop3_b32 v3, v133, v3, 3 bitop3:0x78
	v_lshlrev_b32_e32 v143, 4, v2
	s_add_u32 s6, s22, s20
	v_mov_b32_e32 v2, 0
	v_or_b32_e32 v141, 0x4000, v147
	v_lshlrev_b32_e32 v145, 4, v3
	s_addc_u32 s7, s23, s21
	s_mov_b32 s80, 0
	s_mov_b64 s[22:23], 0
	v_mov_b32_e32 v3, v2
	v_mov_b32_e32 v4, v2
	v_mov_b32_e32 v5, v2
	v_mov_b32_e32 v6, v2
	v_mov_b32_e32 v7, v2
	v_mov_b32_e32 v8, v2
	v_mov_b32_e32 v9, v2
	v_mov_b32_e32 v10, v2
	v_mov_b32_e32 v11, v2
	v_mov_b32_e32 v12, v2
	v_mov_b32_e32 v13, v2
	v_mov_b32_e32 v14, v2
	v_mov_b32_e32 v15, v2
	v_mov_b32_e32 v16, v2
	v_mov_b32_e32 v17, v2
	v_mov_b32_e32 v18, v2
	v_mov_b32_e32 v19, v2
	v_mov_b32_e32 v20, v2
	v_mov_b32_e32 v21, v2
	v_mov_b32_e32 v22, v2
	v_mov_b32_e32 v23, v2
	v_mov_b32_e32 v24, v2
	v_mov_b32_e32 v25, v2
	v_mov_b32_e32 v26, v2
	v_mov_b32_e32 v27, v2
	v_mov_b32_e32 v28, v2
	v_mov_b32_e32 v29, v2
	v_mov_b32_e32 v30, v2
	v_mov_b32_e32 v31, v2
	v_mov_b32_e32 v32, v2
	v_mov_b32_e32 v33, v2
	v_mov_b32_e32 v34, v2
	v_mov_b32_e32 v35, v2
	v_mov_b32_e32 v36, v2
	v_mov_b32_e32 v37, v2
	v_mov_b32_e32 v38, v2
	v_mov_b32_e32 v39, v2
	v_mov_b32_e32 v40, v2
	v_mov_b32_e32 v41, v2
	v_mov_b32_e32 v42, v2
	v_mov_b32_e32 v43, v2
	v_mov_b32_e32 v44, v2
	v_mov_b32_e32 v45, v2
	v_mov_b32_e32 v46, v2
	v_mov_b32_e32 v47, v2
	v_mov_b32_e32 v48, v2
	v_mov_b32_e32 v49, v2
	v_mov_b32_e32 v50, v2
	v_mov_b32_e32 v51, v2
	v_mov_b32_e32 v52, v2
	v_mov_b32_e32 v53, v2
	v_mov_b32_e32 v54, v2
	v_mov_b32_e32 v55, v2
	v_mov_b32_e32 v56, v2
	v_mov_b32_e32 v57, v2
	v_mov_b32_e32 v58, v2
	v_mov_b32_e32 v59, v2
	v_mov_b32_e32 v60, v2
	v_mov_b32_e32 v61, v2
	v_mov_b32_e32 v62, v2
	v_mov_b32_e32 v63, v2
	v_mov_b32_e32 v64, v2
	v_mov_b32_e32 v65, v2
	v_mov_b32_e32 v66, v2
	v_mov_b32_e32 v67, v2
	v_mov_b32_e32 v68, v2
	v_mov_b32_e32 v69, v2
	v_mov_b32_e32 v70, v2
	v_mov_b32_e32 v71, v2
	v_mov_b32_e32 v72, v2
	v_mov_b32_e32 v73, v2
	v_mov_b32_e32 v74, v2
	v_mov_b32_e32 v75, v2
	v_mov_b32_e32 v76, v2
	v_mov_b32_e32 v77, v2
	v_mov_b32_e32 v78, v2
	v_mov_b32_e32 v79, v2
	v_mov_b32_e32 v80, v2
	v_mov_b32_e32 v81, v2
	v_mov_b32_e32 v82, v2
	v_mov_b32_e32 v83, v2
	v_mov_b32_e32 v84, v2
	v_mov_b32_e32 v85, v2
	v_mov_b32_e32 v86, v2
	v_mov_b32_e32 v87, v2
	v_mov_b32_e32 v88, v2
	v_mov_b32_e32 v89, v2
	v_mov_b32_e32 v90, v2
	v_mov_b32_e32 v91, v2
	v_mov_b32_e32 v92, v2
	v_mov_b32_e32 v93, v2
	v_mov_b32_e32 v94, v2
	v_mov_b32_e32 v95, v2
	v_mov_b32_e32 v96, v2
	v_mov_b32_e32 v97, v2
	v_mov_b32_e32 v98, v2
	v_mov_b32_e32 v99, v2
	v_mov_b32_e32 v100, v2
	v_mov_b32_e32 v101, v2
	v_mov_b32_e32 v102, v2
	v_mov_b32_e32 v103, v2
	v_mov_b32_e32 v104, v2
	v_mov_b32_e32 v105, v2
	v_mov_b32_e32 v106, v2
	v_mov_b32_e32 v107, v2
	v_mov_b32_e32 v108, v2
	v_mov_b32_e32 v109, v2
	v_mov_b32_e32 v110, v2
	v_mov_b32_e32 v111, v2
	v_mov_b32_e32 v112, v2
	v_mov_b32_e32 v113, v2
	v_mov_b32_e32 v114, v2
	v_mov_b32_e32 v115, v2
	v_mov_b32_e32 v116, v2
	v_mov_b32_e32 v117, v2
	v_mov_b32_e32 v118, v2
	v_mov_b32_e32 v119, v2
	v_mov_b32_e32 v120, v2
	v_mov_b32_e32 v121, v2
	v_mov_b32_e32 v122, v2
	v_mov_b32_e32 v123, v2
	v_mov_b32_e32 v124, v2
	v_mov_b32_e32 v125, v2
	v_mov_b32_e32 v126, v2
	v_mov_b32_e32 v127, v2
	v_mov_b32_e32 v128, v2
	v_mov_b32_e32 v129, v2
	v_lshlrev_b32_e32 v191, 4, v200
.LBB0_118:
	s_cmp_gt_i32 s80, 0
	s_cselect_b32 s81, -1, 2
	s_add_i32 s81, s81, s80
	s_mulk_i32 s81, 0x6000
	s_add_u32 s82, s6, s22
	s_addc_u32 s83, s7, s23
	s_add_i32 s84, s59, s81
	s_cmp_eq_u32 s22, 0
	s_cbranch_scc1 .Lhyb_first_up
	s_waitcnt vmcnt(0)
	s_barrier
	s_add_i32 s98, s80, 1
	s_cmp_lg_u32 s80, 2
	s_cselect_b32 s98, s98, 0
	s_mul_i32 s98, s98, 0x6000
	s_add_i32 s99, s59, s98
	v_add_u32_e32 v238, s99, v191
	ds_write_b128 v238, v[214:217]
	s_add_i32 s99, s58, s98
	v_add_u32_e32 v190, s99, v191
	ds_write_b128 v190, v[218:221]
	s_add_i32 s99, s57, s98
	v_add_u32_e32 v238, s99, v191
	ds_write_b128 v238, v[222:225]
	s_add_i32 s99, s56, s98
	v_add_u32_e32 v190, s99, v191
	ds_write_b128 v190, v[226:229]
	s_add_i32 s99, s55, s98
	s_addk_i32 s99, 0x4000
	v_add_u32_e32 v238, s99, v191
	ds_write_b128 v238, v[230:233]
	s_add_i32 s99, s54, s98
	s_addk_i32 s99, 0x4000
	v_add_u32_e32 v190, s99, v191
	ds_write_b128 v190, v[234:237]
	s_branch .Lhyb_issue_up

; template <int MI>
; DEV void g2_issue(const bf16_t* __restrict__ abase, const bf16_t* __restrict__ bbase, size_t lda, size_t ldb, unsigned voffa, unsigned voffb,
;                   char* st, int w) {
;   const unsigned base = (unsigned)(size_t)st;
; #pragma unroll
;   for (int c = 0; c < MI; ++c) {
;     const int j = w * MI + c;
;     dma16s(abase + (size_t)(16 * j) * lda, voffa, __builtin_amdgcn_readfirstlane(base + j * 1024));
;   }
; #pragma unroll
;   for (int c = 0; c < 2; ++c) {
;     const int j = w * 2 + c;
;     dma16s(bbase + (size_t)(16 * j) * ldb, voffb, __builtin_amdgcn_readfirstlane(base + 16384 + j * 1024));
;   }
; }
.Lhyb_issue_up:
	s_cmpk_eq_i32 s22, 0xf80
	s_cbranch_scc1 .Lhyb_comp_up
	s_mov_b32 m0, s84
	s_nop 0
	global_load_lds_dwordx4 v1, s[82:83]
	global_load_dwordx4 v[214:217], v1, s[82:83] offset:64
	s_add_u32 s82, s78, s22
	s_addc_u32 s83, s79, s23
	s_add_i32 s84, s58, s81
	s_mov_b32 m0, s84
	s_nop 0
	global_load_lds_dwordx4 v1, s[82:83]
	global_load_dwordx4 v[218:221], v1, s[82:83] offset:64
	s_add_u32 s82, s76, s22
	s_addc_u32 s83, s77, s23
	s_add_i32 s84, s57, s81
	s_mov_b32 m0, s84
	s_nop 0
	global_load_lds_dwordx4 v1, s[82:83]
	global_load_dwordx4 v[222:225], v1, s[82:83] offset:64
	s_add_u32 s82, s74, s22
	s_addc_u32 s83, s75, s23
	s_add_i32 s84, s56, s81
	s_addk_i32 s81, 0x4000
	s_mov_b32 m0, s84
	s_nop 0
	global_load_lds_dwordx4 v1, s[82:83]
	global_load_dwordx4 v[226:229], v1, s[82:83] offset:64
	s_add_u32 s82, s63, s22
	s_addc_u32 s83, s64, s23
	s_add_i32 s84, s81, s55
	s_mov_b32 m0, s84
	s_nop 0
	global_load_lds_dwordx4 v1, s[82:83]
	global_load_dwordx4 v[230:233], v1, s[82:83] offset:64
	s_add_u32 s82, s60, s22
	s_addc_u32 s83, s61, s23
	s_add_i32 s81, s81, s54
	s_mov_b32 m0, s81
	s_nop 0
	global_load_lds_dwordx4 v1, s[82:83]
	global_load_dwordx4 v[234:237], v1, s[82:83] offset:64
;     ...
;     const unsigned so = (unsigned)(stg * G2_STAGE);
;     __builtin_amdgcn_s_setprio(1);
; #pragma unroll
;     for (int ks = 0; ks < 2; ++ks) {
;       const unsigned aa = (ks ? la1 : la0) + so, bb = (ks ? lb1 : lb0) + so;
;       bf16x8 fb0, fb1, fa0, fa1, fa2, fa3;
;       asm volatile("ds_read_b128 %0, %1" : "=v"(fb0) : "v"(bb));
;       asm volatile("ds_read_b128 %0, %1 offset:2048" : "=v"(fb1) : "v"(bb));
;       asm volatile("ds_read_b128 %0, %1" : "=v"(fa0) : "v"(aa));
;       asm volatile("ds_read_b128 %0, %1 offset:2048" : "=v"(fa1) : "v"(aa));
;       if constexpr (MI == 4) {
;         asm volatile("ds_read_b128 %0, %1 offset:4096" : "=v"(fa2) : "v"(aa));
;         asm volatile("ds_read_b128 %0, %1 offset:6144" : "=v"(fa3) : "v"(aa));
;         __builtin_amdgcn_sched_barrier(0);
;         asm volatile("s_waitcnt lgkmcnt(3)" : "+v"(fb0), "+v"(fb1), "+v"(fa0));
;         acc[0][0][0] = mfma(fa0, fb0, acc[0][0][0]); acc[0][0][1] = mfma(fa0, fb1, acc[0][0][1]); __builtin_amdgcn_sched_barrier(0);
;         asm volatile("s_waitcnt lgkmcnt(2)" : "+v"(fa1));
;         acc[0][1][0] = mfma(fa1, fb0, acc[0][1][0]); acc[0][1][1] = mfma(fa1, fb1, acc[0][1][1]); __builtin_amdgcn_sched_barrier(0);
;         asm volatile("s_waitcnt lgkmcnt(1)" : "+v"(fa2));
;         acc[MI / 2 - 1][0][0] = mfma(fa2, fb0, acc[MI / 2 - 1][0][0]); acc[MI / 2 - 1][0][1] = mfma(fa2, fb1, acc[MI / 2 - 1][0][1]); __builtin_amdgcn_sched_barrier(0);
;         asm volatile("s_waitcnt lgkmcnt(0)" : "+v"(fa3));
;         acc[MI / 2 - 1][1][0] = mfma(fa3, fb0, acc[MI / 2 - 1][1][0]); acc[MI / 2 - 1][1][1] = mfma(fa3, fb1, acc[MI / 2 - 1][1][1]); __builtin_amdgcn_sched_barrier(0);
;       } else {
;         __builtin_amdgcn_sched_barrier(0);
;         asm volatile("s_waitcnt lgkmcnt(1)" : "+v"(fb0), "+v"(fb1), "+v"(fa0));
;         acc[0][0][0] = mfma(fa0, fb0, acc[0][0][0]); acc[0][0][1] = mfma(fa0, fb1, acc[0][0][1]); __builtin_amdgcn_sched_barrier(0);
;         asm volatile("s_waitcnt lgkmcnt(0)" : "+v"(fa1));
;         acc[0][1][0] = mfma(fa1, fb0, acc[0][1][0]); acc[0][1][1] = mfma(fa1, fb1, acc[0][1][1]); __builtin_amdgcn_sched_barrier(0);
;       }
;     }
;     __builtin_amdgcn_s_setprio(0);
;     stg = stg == 2 ? 0 : stg + 1;
;   }
;   __syncthreads();
;   if (has_next) {
;     const bf16_t* agn = uni_ptr(A + (size_t)m0n * lda + kbeg);
.Lhyb_comp_up:
	s_mul_i32 s81, s80, 0x6000
	s_setprio 1
	v_add_u32_e32 v149, s81, v138
	v_add_u32_e32 v176, s81, v141
	v_add_u32_e32 v172, v149, v145
	v_add_u32_e32 v156, v176, v145
	ds_read_b128 v[152:155], v156
	ds_read_b128 v[156:159], v156 offset:2048
	ds_read_b128 v[160:163], v172
	ds_read_b128 v[164:167], v172 offset:2048
	ds_read_b128 v[168:171], v172 offset:4096
	ds_read_b128 v[172:175], v172 offset:6144
	s_nop 0
	s_waitcnt lgkmcnt(3)
	s_nop 0
	v_mfma_f32_32x32x16_bf16 v[114:129], v[160:163], v[152:155], v[114:129]
	v_mfma_f32_32x32x16_bf16 v[98:113], v[160:163], v[156:159], v[98:113]
	s_waitcnt lgkmcnt(2)
	s_nop 0
	v_mfma_f32_32x32x16_bf16 v[82:97], v[164:167], v[152:155], v[82:97]
	v_mfma_f32_32x32x16_bf16 v[66:81], v[164:167], v[156:159], v[66:81]
	s_waitcnt lgkmcnt(1)
	s_nop 0
	v_mfma_f32_32x32x16_bf16 v[50:65], v[168:171], v[152:155], v[50:65]
	v_mfma_f32_32x32x16_bf16 v[34:49], v[168:171], v[156:159], v[34:49]
	s_waitcnt lgkmcnt(0)
	s_nop 0
	v_mfma_f32_32x32x16_bf16 v[18:33], v[172:175], v[152:155], v[18:33]
	v_mfma_f32_32x32x16_bf16 v[2:17], v[172:175], v[156:159], v[2:17]
	v_add_u32_e32 v156, v176, v143
	v_add_u32_e32 v149, v149, v143
	ds_read_b128 v[152:155], v156
	ds_read_b128 v[156:159], v156 offset:2048
	ds_read_b128 v[160:163], v149
	ds_read_b128 v[164:167], v149 offset:2048
	ds_read_b128 v[168:171], v149 offset:4096
	ds_read_b128 v[172:175], v149 offset:6144
	s_nop 0
	s_waitcnt lgkmcnt(3)
	s_nop 0
	v_mfma_f32_32x32x16_bf16 v[114:129], v[160:163], v[152:155], v[114:129]
	v_mfma_f32_32x32x16_bf16 v[98:113], v[160:163], v[156:159], v[98:113]
	s_waitcnt lgkmcnt(2)
	s_nop 0
	v_mfma_f32_32x32x16_bf16 v[82:97], v[164:167], v[152:155], v[82:97]
	v_mfma_f32_32x32x16_bf16 v[66:81], v[164:167], v[156:159], v[66:81]
	s_waitcnt lgkmcnt(1)
	s_nop 0
	v_mfma_f32_32x32x16_bf16 v[50:65], v[168:171], v[152:155], v[50:65]
	v_mfma_f32_32x32x16_bf16 v[34:49], v[168:171], v[156:159], v[34:49]
	s_waitcnt lgkmcnt(0)
	s_nop 0
	v_mfma_f32_32x32x16_bf16 v[18:33], v[172:175], v[152:155], v[18:33]
	v_mfma_f32_32x32x16_bf16 v[2:17], v[172:175], v[156:159], v[2:17]
	s_setprio 0
	s_add_i32 s98, s80, 1
	s_cmp_lg_u32 s80, 2
	s_cselect_b32 s80, s98, 0
	s_waitcnt vmcnt(12)
	s_barrier
	s_mul_i32 s81, s80, 0x6000
	s_setprio 1
	v_add_u32_e32 v149, s81, v138
	v_add_u32_e32 v176, s81, v141
	v_add_u32_e32 v172, v149, v145
	v_add_u32_e32 v156, v176, v145
	ds_read_b128 v[152:155], v156
	ds_read_b128 v[156:159], v156 offset:2048
	ds_read_b128 v[160:163], v172
	ds_read_b128 v[164:167], v172 offset:2048
	ds_read_b128 v[168:171], v172 offset:4096
	ds_read_b128 v[172:175], v172 offset:6144
	s_nop 0
	s_waitcnt lgkmcnt(3)
	s_nop 0
	v_mfma_f32_32x32x16_bf16 v[114:129], v[160:163], v[152:155], v[114:129]
	v_mfma_f32_32x32x16_bf16 v[98:113], v[160:163], v[156:159], v[98:113]
	s_waitcnt lgkmcnt(2)
	s_nop 0
	v_mfma_f32_32x32x16_bf16 v[82:97], v[164:167], v[152:155], v[82:97]
	v_mfma_f32_32x32x16_bf16 v[66:81], v[164:167], v[156:159], v[66:81]
	s_waitcnt lgkmcnt(1)
	s_nop 0
	v_mfma_f32_32x32x16_bf16 v[50:65], v[168:171], v[152:155], v[50:65]
	v_mfma_f32_32x32x16_bf16 v[34:49], v[168:171], v[156:159], v[34:49]
	s_waitcnt lgkmcnt(0)
	s_nop 0
	v_mfma_f32_32x32x16_bf16 v[18:33], v[172:175], v[152:155], v[18:33]
	v_mfma_f32_32x32x16_bf16 v[2:17], v[172:175], v[156:159], v[2:17]
	v_add_u32_e32 v156, v176, v143
	v_add_u32_e32 v149, v149, v143
	ds_read_b128 v[152:155], v156
	ds_read_b128 v[156:159], v156 offset:2048
	ds_read_b128 v[160:163], v149
	ds_read_b128 v[164:167], v149 offset:2048
	ds_read_b128 v[168:171], v149 offset:4096
	ds_read_b128 v[172:175], v149 offset:6144
	s_nop 0
	s_waitcnt lgkmcnt(3)
	s_nop 0
	v_mfma_f32_32x32x16_bf16 v[114:129], v[160:163], v[152:155], v[114:129]
	v_mfma_f32_32x32x16_bf16 v[98:113], v[160:163], v[156:159], v[98:113]
	s_waitcnt lgkmcnt(2)
	s_nop 0
	v_mfma_f32_32x32x16_bf16 v[82:97], v[164:167], v[152:155], v[82:97]
	v_mfma_f32_32x32x16_bf16 v[66:81], v[164:167], v[156:159], v[66:81]
	s_waitcnt lgkmcnt(1)
	s_nop 0
	v_mfma_f32_32x32x16_bf16 v[50:65], v[168:171], v[152:155], v[50:65]
	v_mfma_f32_32x32x16_bf16 v[34:49], v[168:171], v[156:159], v[34:49]
	s_waitcnt lgkmcnt(0)
	s_nop 0
	v_mfma_f32_32x32x16_bf16 v[18:33], v[172:175], v[152:155], v[18:33]
	v_mfma_f32_32x32x16_bf16 v[2:17], v[172:175], v[156:159], v[2:17]
	s_add_i32 s98, s80, 1
	s_cmp_lg_u32 s80, 2
	s_cselect_b32 s80, s98, 0
	s_add_u32 s22, s22, 0x80
	s_addc_u32 s23, s23, 0
	s_cmpk_eq_i32 s22, 0x1000
	s_cbranch_scc0 .LBB0_118
	s_setprio 0
	s_and_b64 vcc, exec, s[8:9]
	s_waitcnt lgkmcnt(0)
	s_barrier
	s_cbranch_vccz .LBB0_109
	s_lshl_b32 s6, s52, 8
	s_ashr_i32 s7, s6, 31
	s_lshl_b32 s8, s53, 7
	s_lshl_b64 s[6:7], s[6:7], 12
	s_add_u32 s22, s26, s6
	s_addc_u32 s23, s27, s7
	s_ashr_i32 s9, s8, 31
	s_lshl_b64 s[6:7], s[8:9], 12
	s_add_u32 s60, s28, s6
	s_addc_u32 s61, s30, s7
	s_add_u32 s6, s22, s20
	s_addc_u32 s7, s23, s21
	s_add_u32 s8, s22, s18
	s_addc_u32 s9, s23, s19
	s_add_u32 s16, s22, s16
	s_addc_u32 s17, s23, s17
	s_add_u32 s14, s22, s14
	s_mov_b32 m0, s59
	s_nop 0
	global_load_lds_dwordx4 v1, s[6:7]
	s_addc_u32 s15, s23, s15
	s_mov_b32 m0, s58
	s_nop 0
	global_load_lds_dwordx4 v1, s[8:9]
	s_add_u32 s12, s60, s12
	s_mov_b32 m0, s57
	s_nop 0
	global_load_lds_dwordx4 v1, s[16:17]
	s_addc_u32 s13, s61, s13
	s_add_i32 s18, s55, 0x4000
	s_mov_b32 m0, s56
	s_nop 0
	global_load_lds_dwordx4 v1, s[14:15]
	s_add_u32 s10, s60, s10
	s_mov_b32 m0, s18
	s_nop 0
	global_load_lds_dwordx4 v1, s[12:13]
	s_addc_u32 s11, s61, s11
	s_add_i32 s18, s54, 0x4000
	s_add_u32 s6, s6, 64
	s_mov_b32 m0, s18
	s_nop 0
	global_load_lds_dwordx4 v1, s[10:11]
	s_addc_u32 s7, s7, 0
	s_add_i32 s18, s59, 0x6000
	s_mov_b32 m0, s18
	s_nop 0
	global_load_lds_dwordx4 v1, s[6:7]
	s_add_u32 s6, s8, 64
	s_addc_u32 s7, s9, 0
	s_add_i32 s8, s58, 0x6000
	s_mov_b32 m0, s8
	s_nop 0
	global_load_lds_dwordx4 v1, s[6:7]
	s_add_u32 s6, s16, 64
	s_addc_u32 s7, s17, 0
	s_add_i32 s8, s57, 0x6000
	s_mov_b32 m0, s8
	s_nop 0
	global_load_lds_dwordx4 v1, s[6:7]
	s_add_u32 s6, s14, 64
	s_addc_u32 s7, s15, 0
	s_add_i32 s8, s56, 0x6000
	s_mov_b32 m0, s8
	s_nop 0
	global_load_lds_dwordx4 v1, s[6:7]
	s_add_u32 s6, s12, 64
	s_addc_u32 s7, s13, 0
	s_add_i32 s55, s55, 0xa000
	s_mov_b32 m0, s55
	s_nop 0
	global_load_lds_dwordx4 v1, s[6:7]
	s_add_u32 s6, s10, 64
	s_addc_u32 s7, s11, 0
	s_add_i32 s54, s54, 0xa000
	s_mov_b32 m0, s54
	s_nop 0
	global_load_lds_dwordx4 v1, s[6:7]
	s_branch .LBB0_109

; DEV int otid() { int t = threadIdx.x; asm volatile("" : "+v"(t)); return t; }
;   const int tid = otid(), lane = tid & 63, w = __builtin_amdgcn_readfirstlane(tid >> 6), wm = w >> 1, wn = w & 1, r32 = lane & 31, hh = lane >> 5;
;   f32x16 acc[MI / 2][2][2];
; #pragma unroll
;   for (int h = 0; h < MI / 2; ++h) { acc[h][0][0] = zero16(); acc[h][0][1] = zero16(); acc[h][1][0] = zero16(); acc[h][1][1] = zero16(); }
;   const int lrow = lane >> 2, lp = (lane & 3) ^ ((lane >> 4) & 3);
;   const bf16_t* ag = uni_ptr(A + (size_t)m0 * lda + kbeg);
;   const bf16_t* bg = uni_ptr(Bt + (size_t)n0 * ldb + kbeg);
;   const unsigned voffa = ((unsigned)lrow * (unsigned)lda + (unsigned)lp * 8u) * 2u;
;   const unsigned voffb = ((unsigned)lrow * (unsigned)ldb + (unsigned)lp * 8u) * 2u;
;   const int nk = (kend - kbeg) >> 5;
;   if (!pre) {
;     asm volatile("s_waitcnt vmcnt(0)" ::: "memory");
;     g2_issue<MI>(ag, bg, lda, ldb, voffa, voffb, lds, w);
;     if (nk > 1) g2_issue<MI>(ag + 32, bg + 32, lda, ldb, voffa, voffb, lds + G2_STAGE, w);
;   }
;   const int key = (r32 >> 2) & 3;
;   const int aoff = (wm * (MI * 32) + r32) * 64;
;   const int boff = 16384 + (wn * 64 + r32) * 64;
;   const int p0 = ((0 + hh) ^ key) * 16, p1 = ((2 + hh) ^ key) * 16;
;   const unsigned lbase = (unsigned)(size_t)lds;
;   const unsigned la0 = lbase + aoff + p0, la1 = lbase + aoff + p1, lb0 = lbase + boff + p0, lb1 = lbase + boff + p1;
;   int stg = 0;
.LBB0_156:
	s_xor_b64 s[0:1], s[8:9], -1
	s_and_b32 s3, s55, 0xffffff80
	s_and_b32 s5, s55, 64
	s_lshl_b32 s59, s54, 12
	s_lshl_b32 s58, s56, 10
	s_lshl_b32 s57, s57, 10
	s_lshl_b32 s56, s63, 10
	s_lshl_b32 s55, s54, 11
	s_lshl_b32 s54, s64, 10
	s_add_u32 s20, s60, 0x80
	s_addc_u32 s21, s61, 0
	s_lshl_b64 s[10:11], s[10:11], 1
	s_add_u32 s60, s20, s10
	s_addc_u32 s61, s21, s11
	s_lshl_b64 s[12:13], s[12:13], 1
	s_add_u32 s63, s20, s12
	s_addc_u32 s64, s21, s13
	s_add_u32 s22, s22, 0x80
	s_addc_u32 s23, s23, 0
	s_lshl_b64 s[14:15], s[14:15], 1
	s_add_u32 s74, s22, s14
	s_addc_u32 s75, s23, s15
	s_lshl_b64 s[16:17], s[16:17], 1
	s_add_u32 s76, s22, s16
	v_and_b32_e32 v3, 63, v2
	v_and_b32_e32 v130, 31, v2
	s_addc_u32 s77, s23, s17
	s_lshl_b64 s[18:19], s[18:19], 1
	v_lshrrev_b32_e32 v133, 5, v3
	v_lshrrev_b32_e32 v3, 2, v2
	v_bfe_u32 v2, v2, 2, 2
	v_or_b32_e32 v4, s3, v130
	s_add_u32 s78, s22, s18
	v_lshlrev_b32_e32 v138, 6, v4
	v_or_b32_e32 v4, s5, v130
	v_bitop3_b32 v2, v133, v2, 2 bitop3:0x36
	s_addc_u32 s79, s23, s19
	s_lshl_b64 s[20:21], s[6:7], 1
	v_lshlrev_b32_e32 v147, 6, v4
	v_bitop3_b32 v3, v133, v3, 3 bitop3:0x78
	v_lshlrev_b32_e32 v143, 4, v2
	s_add_u32 s6, s22, s20
	v_mov_b32_e32 v2, 0
	v_or_b32_e32 v141, 0x4000, v147
	v_lshlrev_b32_e32 v145, 4, v3
	s_addc_u32 s7, s23, s21
	s_mov_b32 s80, 0
	s_mov_b64 s[22:23], 0
	v_mov_b32_e32 v3, v2
	v_mov_b32_e32 v4, v2
	v_mov_b32_e32 v5, v2
	v_mov_b32_e32 v6, v2
	v_mov_b32_e32 v7, v2
	v_mov_b32_e32 v8, v2
	v_mov_b32_e32 v9, v2
	v_mov_b32_e32 v10, v2
	v_mov_b32_e32 v11, v2
	v_mov_b32_e32 v12, v2
	v_mov_b32_e32 v13, v2
	v_mov_b32_e32 v14, v2
	v_mov_b32_e32 v15, v2
	v_mov_b32_e32 v16, v2
	v_mov_b32_e32 v17, v2
	v_mov_b32_e32 v18, v2
	v_mov_b32_e32 v19, v2
	v_mov_b32_e32 v20, v2
	v_mov_b32_e32 v21, v2
	v_mov_b32_e32 v22, v2
	v_mov_b32_e32 v23, v2
	v_mov_b32_e32 v24, v2
	v_mov_b32_e32 v25, v2
	v_mov_b32_e32 v26, v2
	v_mov_b32_e32 v27, v2
	v_mov_b32_e32 v28, v2
	v_mov_b32_e32 v29, v2
	v_mov_b32_e32 v30, v2
	v_mov_b32_e32 v31, v2
	v_mov_b32_e32 v32, v2
	v_mov_b32_e32 v33, v2
	v_mov_b32_e32 v34, v2
	v_mov_b32_e32 v35, v2
	v_mov_b32_e32 v36, v2
	v_mov_b32_e32 v37, v2
	v_mov_b32_e32 v38, v2
	v_mov_b32_e32 v39, v2
	v_mov_b32_e32 v40, v2
	v_mov_b32_e32 v41, v2
	v_mov_b32_e32 v42, v2
	v_mov_b32_e32 v43, v2
	v_mov_b32_e32 v44, v2
	v_mov_b32_e32 v45, v2
	v_mov_b32_e32 v46, v2
	v_mov_b32_e32 v47, v2
	v_mov_b32_e32 v48, v2
	v_mov_b32_e32 v49, v2
	v_mov_b32_e32 v50, v2
	v_mov_b32_e32 v51, v2
	v_mov_b32_e32 v52, v2
	v_mov_b32_e32 v53, v2
	v_mov_b32_e32 v54, v2
	v_mov_b32_e32 v55, v2
	v_mov_b32_e32 v56, v2
	v_mov_b32_e32 v57, v2
	v_mov_b32_e32 v58, v2
	v_mov_b32_e32 v59, v2
	v_mov_b32_e32 v60, v2
	v_mov_b32_e32 v61, v2
	v_mov_b32_e32 v62, v2
	v_mov_b32_e32 v63, v2
	v_mov_b32_e32 v64, v2
	v_mov_b32_e32 v65, v2
	v_mov_b32_e32 v66, v2
	v_mov_b32_e32 v67, v2
	v_mov_b32_e32 v68, v2
	v_mov_b32_e32 v69, v2
	v_mov_b32_e32 v70, v2
	v_mov_b32_e32 v71, v2
	v_mov_b32_e32 v72, v2
	v_mov_b32_e32 v73, v2
	v_mov_b32_e32 v74, v2
	v_mov_b32_e32 v75, v2
	v_mov_b32_e32 v76, v2
	v_mov_b32_e32 v77, v2
	v_mov_b32_e32 v78, v2
	v_mov_b32_e32 v79, v2
	v_mov_b32_e32 v80, v2
	v_mov_b32_e32 v81, v2
	v_mov_b32_e32 v82, v2
	v_mov_b32_e32 v83, v2
	v_mov_b32_e32 v84, v2
	v_mov_b32_e32 v85, v2
	v_mov_b32_e32 v86, v2
	v_mov_b32_e32 v87, v2
	v_mov_b32_e32 v88, v2
	v_mov_b32_e32 v89, v2
	v_mov_b32_e32 v90, v2
	v_mov_b32_e32 v91, v2
	v_mov_b32_e32 v92, v2
	v_mov_b32_e32 v93, v2
	v_mov_b32_e32 v94, v2
	v_mov_b32_e32 v95, v2
	v_mov_b32_e32 v96, v2
	v_mov_b32_e32 v97, v2
	v_mov_b32_e32 v98, v2
	v_mov_b32_e32 v99, v2
	v_mov_b32_e32 v100, v2
	v_mov_b32_e32 v101, v2
	v_mov_b32_e32 v102, v2
	v_mov_b32_e32 v103, v2
	v_mov_b32_e32 v104, v2
	v_mov_b32_e32 v105, v2
	v_mov_b32_e32 v106, v2
	v_mov_b32_e32 v107, v2
	v_mov_b32_e32 v108, v2
	v_mov_b32_e32 v109, v2
	v_mov_b32_e32 v110, v2
	v_mov_b32_e32 v111, v2
	v_mov_b32_e32 v112, v2
	v_mov_b32_e32 v113, v2
	v_mov_b32_e32 v114, v2
	v_mov_b32_e32 v115, v2
	v_mov_b32_e32 v116, v2
	v_mov_b32_e32 v117, v2
	v_mov_b32_e32 v118, v2
	v_mov_b32_e32 v119, v2
	v_mov_b32_e32 v120, v2
	v_mov_b32_e32 v121, v2
	v_mov_b32_e32 v122, v2
	v_mov_b32_e32 v123, v2
	v_mov_b32_e32 v124, v2
	v_mov_b32_e32 v125, v2
	v_mov_b32_e32 v126, v2
	v_mov_b32_e32 v127, v2
	v_mov_b32_e32 v128, v2
	v_mov_b32_e32 v129, v2
	v_lshlrev_b32_e32 v191, 4, v200

;     ...
;     const unsigned so = (unsigned)(stg * G2_STAGE);
;     __builtin_amdgcn_s_setprio(1);
; #pragma unroll
;     for (int ks = 0; ks < 2; ++ks) {
;       const unsigned aa = (ks ? la1 : la0) + so, bb = (ks ? lb1 : lb0) + so;
;       bf16x8 fb0, fb1, fa0, fa1, fa2, fa3;
;       asm volatile("ds_read_b128 %0, %1" : "=v"(fb0) : "v"(bb));
;       asm volatile("ds_read_b128 %0, %1 offset:2048" : "=v"(fb1) : "v"(bb));
;       asm volatile("ds_read_b128 %0, %1" : "=v"(fa0) : "v"(aa));
;       asm volatile("ds_read_b128 %0, %1 offset:2048" : "=v"(fa1) : "v"(aa));
;       if constexpr (MI == 4) {
;         asm volatile("ds_read_b128 %0, %1 offset:4096" : "=v"(fa2) : "v"(aa));
;         asm volatile("ds_read_b128 %0, %1 offset:6144" : "=v"(fa3) : "v"(aa));
;         __builtin_amdgcn_sched_barrier(0);
;         asm volatile("s_waitcnt lgkmcnt(3)" : "+v"(fb0), "+v"(fb1), "+v"(fa0));
;         acc[0][0][0] = mfma(fa0, fb0, acc[0][0][0]); acc[0][0][1] = mfma(fa0, fb1, acc[0][0][1]); __builtin_amdgcn_sched_barrier(0);
;         asm volatile("s_waitcnt lgkmcnt(2)" : "+v"(fa1));
;         acc[0][1][0] = mfma(fa1, fb0, acc[0][1][0]); acc[0][1][1] = mfma(fa1, fb1, acc[0][1][1]); __builtin_amdgcn_sched_barrier(0);
;         asm volatile("s_waitcnt lgkmcnt(1)" : "+v"(fa2));
;         acc[MI / 2 - 1][0][0] = mfma(fa2, fb0, acc[MI / 2 - 1][0][0]); acc[MI / 2 - 1][0][1] = mfma(fa2, fb1, acc[MI / 2 - 1][0][1]); __builtin_amdgcn_sched_barrier(0);
;         asm volatile("s_waitcnt lgkmcnt(0)" : "+v"(fa3));
;         acc[MI / 2 - 1][1][0] = mfma(fa3, fb0, acc[MI / 2 - 1][1][0]); acc[MI / 2 - 1][1][1] = mfma(fa3, fb1, acc[MI / 2 - 1][1][1]); __builtin_amdgcn_sched_barrier(0);
;       } else {
;         __builtin_amdgcn_sched_barrier(0);
;         asm volatile("s_waitcnt lgkmcnt(1)" : "+v"(fb0), "+v"(fb1), "+v"(fa0));
;         acc[0][0][0] = mfma(fa0, fb0, acc[0][0][0]); acc[0][0][1] = mfma(fa0, fb1, acc[0][0][1]); __builtin_amdgcn_sched_barrier(0);
;         asm volatile("s_waitcnt lgkmcnt(0)" : "+v"(fa1));
;         acc[0][1][0] = mfma(fa1, fb0, acc[0][1][0]); acc[0][1][1] = mfma(fa1, fb1, acc[0][1][1]); __builtin_amdgcn_sched_barrier(0);
;       }
;     }
;     __builtin_amdgcn_s_setprio(0);
;     stg = stg == 2 ? 0 : stg + 1;
;   }
;   __syncthreads();
;   if (has_next) {
;     const bf16_t* agn = uni_ptr(A + (size_t)m0n * lda + kbeg);
.Lhyb_comp_proj:
	s_mul_i32 s81, s80, 0x6000
	s_setprio 1
	v_add_u32_e32 v149, s81, v138
	v_add_u32_e32 v176, s81, v141
	v_add_u32_e32 v172, v149, v145
	v_add_u32_e32 v156, v176, v145
	ds_read_b128 v[152:155], v156
	ds_read_b128 v[156:159], v156 offset:2048
	ds_read_b128 v[160:163], v172
	ds_read_b128 v[164:167], v172 offset:2048
	ds_read_b128 v[168:171], v172 offset:4096
	ds_read_b128 v[172:175], v172 offset:6144
	s_nop 0
	s_waitcnt lgkmcnt(3)
	s_nop 0
	v_mfma_f32_32x32x16_bf16 v[114:129], v[160:163], v[152:155], v[114:129]
	v_mfma_f32_32x32x16_bf16 v[98:113], v[160:163], v[156:159], v[98:113]
	s_waitcnt lgkmcnt(2)
	s_nop 0
	v_mfma_f32_32x32x16_bf16 v[82:97], v[164:167], v[152:155], v[82:97]
	v_mfma_f32_32x32x16_bf16 v[66:81], v[164:167], v[156:159], v[66:81]
	s_waitcnt lgkmcnt(1)
	s_nop 0
	v_mfma_f32_32x32x16_bf16 v[50:65], v[168:171], v[152:155], v[50:65]
	v_mfma_f32_32x32x16_bf16 v[34:49], v[168:171], v[156:159], v[34:49]
	s_waitcnt lgkmcnt(0)
	s_nop 0
	v_mfma_f32_32x32x16_bf16 v[18:33], v[172:175], v[152:155], v[18:33]
	v_mfma_f32_32x32x16_bf16 v[2:17], v[172:175], v[156:159], v[2:17]
	v_add_u32_e32 v156, v176, v143
	v_add_u32_e32 v149, v149, v143
	ds_read_b128 v[152:155], v156
	ds_read_b128 v[156:159], v156 offset:2048
	ds_read_b128 v[160:163], v149
	ds_read_b128 v[164:167], v149 offset:2048
	ds_read_b128 v[168:171], v149 offset:4096
	ds_read_b128 v[172:175], v149 offset:6144
	s_nop 0
	s_waitcnt lgkmcnt(3)
	s_nop 0
	v_mfma_f32_32x32x16_bf16 v[114:129], v[160:163], v[152:155], v[114:129]
	v_mfma_f32_32x32x16_bf16 v[98:113], v[160:163], v[156:159], v[98:113]
	s_waitcnt lgkmcnt(2)
	s_nop 0
	v_mfma_f32_32x32x16_bf16 v[82:97], v[164:167], v[152:155], v[82:97]
	v_mfma_f32_32x32x16_bf16 v[66:81], v[164:167], v[156:159], v[66:81]
	s_waitcnt lgkmcnt(1)
	s_nop 0
	v_mfma_f32_32x32x16_bf16 v[50:65], v[168:171], v[152:155], v[50:65]
	v_mfma_f32_32x32x16_bf16 v[34:49], v[168:171], v[156:159], v[34:49]
	s_waitcnt lgkmcnt(0)
	s_nop 0
	v_mfma_f32_32x32x16_bf16 v[18:33], v[172:175], v[152:155], v[18:33]
	v_mfma_f32_32x32x16_bf16 v[2:17], v[172:175], v[156:159], v[2:17]
	s_setprio 0
	s_add_i32 s98, s80, 1
	s_cmp_lg_u32 s80, 2
	s_cselect_b32 s80, s98, 0
	s_waitcnt vmcnt(12)
	s_barrier
	s_mul_i32 s81, s80, 0x6000
	s_setprio 1
	v_add_u32_e32 v149, s81, v138
	v_add_u32_e32 v176, s81, v141
	v_add_u32_e32 v172, v149, v145
	v_add_u32_e32 v156, v176, v145
	ds_read_b128 v[152:155], v156
	ds_read_b128 v[156:159], v156 offset:2048
	ds_read_b128 v[160:163], v172
	ds_read_b128 v[164:167], v172 offset:2048
	ds_read_b128 v[168:171], v172 offset:4096
	ds_read_b128 v[172:175], v172 offset:6144
	s_nop 0
	s_waitcnt lgkmcnt(3)
	s_nop 0
	v_mfma_f32_32x32x16_bf16 v[114:129], v[160:163], v[152:155], v[114:129]
	v_mfma_f32_32x32x16_bf16 v[98:113], v[160:163], v[156:159], v[98:113]
	s_waitcnt lgkmcnt(2)
	s_nop 0
	v_mfma_f32_32x32x16_bf16 v[82:97], v[164:167], v[152:155], v[82:97]
	v_mfma_f32_32x32x16_bf16 v[66:81], v[164:167], v[156:159], v[66:81]
	s_waitcnt lgkmcnt(1)
	s_nop 0
	v_mfma_f32_32x32x16_bf16 v[50:65], v[168:171], v[152:155], v[50:65]
	v_mfma_f32_32x32x16_bf16 v[34:49], v[168:171], v[156:159], v[34:49]
	s_waitcnt lgkmcnt(0)
	s_nop 0
	v_mfma_f32_32x32x16_bf16 v[18:33], v[172:175], v[152:155], v[18:33]
	v_mfma_f32_32x32x16_bf16 v[2:17], v[172:175], v[156:159], v[2:17]
	v_add_u32_e32 v156, v176, v143
	v_add_u32_e32 v149, v149, v143
	ds_read_b128 v[152:155], v156
	ds_read_b128 v[156:159], v156 offset:2048
	ds_read_b128 v[160:163], v149
	ds_read_b128 v[164:167], v149 offset:2048
	ds_read_b128 v[168:171], v149 offset:4096
	ds_read_b128 v[172:175], v149 offset:6144
	s_nop 0
	s_waitcnt lgkmcnt(3)
	s_nop 0
	v_mfma_f32_32x32x16_bf16 v[114:129], v[160:163], v[152:155], v[114:129]
	v_mfma_f32_32x32x16_bf16 v[98:113], v[160:163], v[156:159], v[98:113]
	s_waitcnt lgkmcnt(2)
	s_nop 0
	v_mfma_f32_32x32x16_bf16 v[82:97], v[164:167], v[152:155], v[82:97]
	v_mfma_f32_32x32x16_bf16 v[66:81], v[164:167], v[156:159], v[66:81]
	s_waitcnt lgkmcnt(1)
	s_nop 0
	v_mfma_f32_32x32x16_bf16 v[50:65], v[168:171], v[152:155], v[50:65]
	v_mfma_f32_32x32x16_bf16 v[34:49], v[168:171], v[156:159], v[34:49]
	s_waitcnt lgkmcnt(0)
	s_nop 0
	v_mfma_f32_32x32x16_bf16 v[18:33], v[172:175], v[152:155], v[18:33]
	v_mfma_f32_32x32x16_bf16 v[2:17], v[172:175], v[156:159], v[2:17]
	s_add_i32 s98, s80, 1
	s_cmp_lg_u32 s80, 2
	s_cselect_b32 s80, s98, 0
	s_add_u32 s22, s22, 0x80
	s_addc_u32 s23, s23, 0
	s_cmpk_eq_i32 s22, 0x1000
	s_cbranch_scc0 .LBB0_157
	s_setprio 0
	s_and_b64 vcc, exec, s[8:9]
	s_waitcnt lgkmcnt(0)
	s_barrier
	s_cbranch_vccz .LBB0_145
	s_lshl_b32 s6, s25, 8
	s_ashr_i32 s7, s6, 31
	s_lshl_b32 s8, s26, 7
	s_lshl_b64 s[6:7], s[6:7], 12
	s_add_u32 s22, s27, s6
	s_addc_u32 s23, s28, s7
	s_ashr_i32 s9, s8, 31
	s_lshl_b64 s[6:7], s[8:9], 12
	s_add_u32 s60, s30, s6
	s_addc_u32 s61, s31, s7
	s_add_u32 s6, s22, s20
	s_addc_u32 s7, s23, s21
	s_add_u32 s8, s22, s18
	s_addc_u32 s9, s23, s19
	s_add_u32 s16, s22, s16
	s_addc_u32 s17, s23, s17
	s_add_u32 s14, s22, s14
	s_mov_b32 m0, s59
	s_nop 0
	global_load_lds_dwordx4 v1, s[6:7]
	s_addc_u32 s15, s23, s15
	s_mov_b32 m0, s58
	s_nop 0
	global_load_lds_dwordx4 v1, s[8:9]
	s_add_u32 s12, s60, s12
	s_mov_b32 m0, s57
	s_nop 0
	global_load_lds_dwordx4 v1, s[16:17]
	s_addc_u32 s13, s61, s13
	s_add_i32 s18, s55, 0x4000
	s_mov_b32 m0, s56
	s_nop 0
	global_load_lds_dwordx4 v1, s[14:15]
	s_add_u32 s10, s60, s10
	s_mov_b32 m0, s18
	s_nop 0
	global_load_lds_dwordx4 v1, s[12:13]
	s_addc_u32 s11, s61, s11
	s_add_i32 s18, s54, 0x4000
	s_add_u32 s6, s6, 64
	s_mov_b32 m0, s18
	s_nop 0
	global_load_lds_dwordx4 v1, s[10:11]
	s_addc_u32 s7, s7, 0
	s_add_i32 s18, s59, 0x6000
	s_mov_b32 m0, s18
	s_nop 0
	global_load_lds_dwordx4 v1, s[6:7]
	s_add_u32 s6, s8, 64
	s_addc_u32 s7, s9, 0
	s_add_i32 s8, s58, 0x6000
	s_mov_b32 m0, s8
	s_nop 0
	global_load_lds_dwordx4 v1, s[6:7]
	s_add_u32 s6, s16, 64
	s_addc_u32 s7, s17, 0
	s_add_i32 s8, s57, 0x6000
	s_mov_b32 m0, s8
	s_nop 0
	global_load_lds_dwordx4 v1, s[6:7]
	s_add_u32 s6, s14, 64
	s_addc_u32 s7, s15, 0
	s_add_i32 s8, s56, 0x6000
	s_mov_b32 m0, s8
	s_nop 0
	global_load_lds_dwordx4 v1, s[6:7]
	s_add_u32 s6, s12, 64
	s_addc_u32 s7, s13, 0
	s_add_i32 s55, s55, 0xa000
	s_mov_b32 m0, s55
	s_nop 0
	global_load_lds_dwordx4 v1, s[6:7]
	s_add_u32 s6, s10, 64
	s_addc_u32 s7, s11, 0
	s_add_i32 s54, s54, 0xa000
	s_mov_b32 m0, s54
	s_nop 0
	global_load_lds_dwordx4 v1, s[6:7]
	s_branch .LBB0_145

; template <int MODE, int DQK>
; DEV void flash_half(FlashState& s, f32x16* imp, const bf16x8* qf, const char* st, int kh, int kb, int qpos, float cq,
;                     const float* __restrict__ cumk, bool selbit, float c2, float invl, int r32, int hh, int wqmin_, int wqmax_) {
;   f32x16 S = zero16();
;   const int pr32 = pi32(r32);
;   const char* kp = st + (kh * 32 + pr32) * (DQK * 2);
;   const int kkey = (DQK == 128) ? (pr32 & 15) : ((pr32 >> 1) & 7);
; #pragma unroll
;   for (int ks = 0; ks < DQK / 16; ++ks) { bf16x8 kf = *(const bf16x8*)(kp + (((ks * 2 + hh) ^ kkey) << 4)); S = mfma(kf, qf[ks], S); }
;   const int kbase = kb + 8 * hh;
;   float pr[16];
;   if (MODE == M_SB) {
;     float lk[16];
;     float Tlo = 0.f, Thi = 0.f;
; #pragma unroll
;     for (int r = 0; r < 16; ++r) {
;       int key = kbase + r + (r >= 8 ? 8 : 0);
;       float z2 = S[r] * c2;
;       float sp2 = fmaxf(z2, 0.f) + lg2(1.f + ex2(-fabsf(z2)));
;       lk[r] = (key < qpos) ? -sp2 : 0.f;
;       if (r < 8) Tlo += lk[r]; else Thi += lk[r];
;     }
;     float Plo = __shfl_xor(Tlo, 32), Phi = __shfl_xor(Thi, 32);
;     float baseLo = s.R + Thi + Phi + (hh == 0 ? Plo : 0.f);
;     float baseHi = s.R + (hh == 0 ? Phi : 0.f);
;     float run = 0.f;
; #pragma unroll
;     for (int r = 7; r >= 0; --r) { pr[r] = (kbase + r < qpos) ? ex2(S[r] * c2 + lk[r] + baseLo + run) : 0.f; run += lk[r]; }
;     run = 0.f;
; #pragma unroll
;     for (int r = 15; r >= 8; --r) { pr[r] = (kbase + r + 8 < qpos) ? ex2(S[r] * c2 + lk[r] + baseHi + run) : 0.f; run += lk[r]; }
;     s.R += Tlo + Thi + Plo + Phi;
;   } else {
;     float t[16];
;     float ck[16];
;     if (MODE == M_FOX) {
;       const float* cl = (const float*)(st + 32768) + kh * 32 + 8 * hh;
;       float4 a0 = *(const float4*)(cl), a1 = *(const float4*)(cl + 4);
;       float4 a2 = *(const float4*)(cl + 16), a3 = *(const float4*)(cl + 20);
;       ck[0] = a0.x; ck[1] = a0.y; ck[2] = a0.z; ck[3] = a0.w; ck[4] = a1.x; ck[5] = a1.y; ck[6] = a1.z; ck[7] = a1.w;
;       ck[8] = a2.x; ck[9] = a2.y; ck[10] = a2.z; ck[11] = a2.w; ck[12] = a3.x; ck[13] = a3.y; ck[14] = a3.z; ck[15] = a3.w;
;     }
;     float tmax = -__builtin_inff();
;     bool nomask = (kb + 31 <= wqmin_);
;     if (MODE == M_WIN) nomask = nomask && (kb > wqmax_ - 512);
;     if (MODE == M_SLC) nomask = nomask && __all(selbit);
.LBB0_199:
	s_lshl_b32 s6, s6, 6
	v_cmp_le_i32_e32 vcc, s6, v133
	s_and_saveexec_b64 s[12:13], vcc
	s_cbranch_execz .LBB0_201
	s_mul_i32 s7, s19, 0x8100
	v_add_u32_e32 v39, s7, v29
	v_add_u32_e32 v46, v39, v30
	ds_read_b128 v[2:5], v46
	v_add_u32_e32 v45, v39, v31
	ds_read_b128 v[18:21], v45
	v_add_u32_e32 v44, v39, v32
	v_add_u32_e32 v43, v39, v33
	v_or_b32_e32 v41, s6, v38
	v_cmp_le_i32_e32 vcc, v41, v127
	v_or_b32_e32 v40, 2, v41
	s_waitcnt lgkmcnt(0)
	v_mfma_f32_32x32x16_bf16 v[2:17], v[2:5], v[82:85], 0
	v_mfma_f32_32x32x16_bf16 v[2:17], v[18:21], v[86:89], v[2:17]
	ds_read_b128 v[18:21], v44
	s_waitcnt lgkmcnt(0)
	v_mfma_f32_32x32x16_bf16 v[2:17], v[18:21], v[90:93], v[2:17]
	ds_read_b128 v[18:21], v43
	s_waitcnt lgkmcnt(0)
	v_mfma_f32_32x32x16_bf16 v[2:17], v[18:21], v[94:97], v[2:17]
	v_add_u32_e32 v21, v39, v34
	ds_read_b128 v[48:51], v21
	v_add_u32_e32 v20, v39, v35
	v_add_u32_e32 v19, v39, v36
	v_add_u32_e32 v18, v39, v37
	s_waitcnt lgkmcnt(0)
	v_mfma_f32_32x32x16_bf16 v[2:17], v[48:51], v[98:101], v[2:17]
	ds_read_b128 v[48:51], v20
	s_waitcnt lgkmcnt(0)
	v_mfma_f32_32x32x16_bf16 v[2:17], v[48:51], v[102:105], v[2:17]
	ds_read_b128 v[48:51], v19
	s_waitcnt lgkmcnt(0)
	v_mfma_f32_32x32x16_bf16 v[2:17], v[48:51], v[106:109], v[2:17]
	ds_read_b128 v[48:51], v18
	s_waitcnt lgkmcnt(0)
	v_mfma_f32_32x32x16_bf16 v[2:17], v[48:51], v[110:113], v[2:17]
	s_nop 11
	v_mul_f32_e32 v2, 0x3e0293ee, v2
	v_cndmask_b32_e32 v2, v210, v2, vcc
	v_cmp_lt_i32_e32 vcc, v41, v127
	v_mul_f32_e32 v3, 0x3e0293ee, v3
	v_mul_f32_e32 v4, 0x3e0293ee, v4
	v_cndmask_b32_e32 v3, v210, v3, vcc
	v_cmp_le_i32_e32 vcc, v40, v127
	v_or_b32_e32 v40, 3, v41
	v_mul_f32_e32 v5, 0x3e0293ee, v5
	v_cndmask_b32_e32 v4, v210, v4, vcc
	v_cmp_le_i32_e32 vcc, v40, v127
	v_or_b32_e32 v40, 4, v41
	v_mul_f32_e32 v6, 0x3e0293ee, v6
	v_cndmask_b32_e32 v5, v210, v5, vcc
	v_cmp_le_i32_e32 vcc, v40, v127
	v_or_b32_e32 v40, 5, v41
	v_mul_f32_e32 v7, 0x3e0293ee, v7
	v_cndmask_b32_e32 v6, v210, v6, vcc
	v_cmp_le_i32_e32 vcc, v40, v127
	v_or_b32_e32 v40, 6, v41
	v_mul_f32_e32 v8, 0x3e0293ee, v8
	v_cndmask_b32_e32 v7, v210, v7, vcc
	v_cmp_le_i32_e32 vcc, v40, v127
	v_or_b32_e32 v40, 7, v41
	v_mul_f32_e32 v9, 0x3e0293ee, v9
	v_cndmask_b32_e32 v8, v210, v8, vcc
	v_cmp_le_i32_e32 vcc, v40, v127
	v_or_b32_e32 v40, 16, v41
	v_mul_f32_e32 v10, 0x3e0293ee, v10
	v_cndmask_b32_e32 v9, v210, v9, vcc
	v_cmp_le_i32_e32 vcc, v40, v127
	v_or_b32_e32 v40, 17, v41
	v_mul_f32_e32 v11, 0x3e0293ee, v11
	v_cndmask_b32_e32 v10, v210, v10, vcc
	v_cmp_le_i32_e32 vcc, v40, v127
	v_or_b32_e32 v40, 18, v41
	v_max3_f32 v39, v2, s89, v3
	v_cndmask_b32_e32 v11, v210, v11, vcc
	v_mul_f32_e32 v12, 0x3e0293ee, v12
	v_cmp_le_i32_e32 vcc, v40, v127
	v_or_b32_e32 v40, 19, v41
	v_max3_f32 v39, v39, v4, v5
	v_cndmask_b32_e32 v12, v210, v12, vcc
	v_mul_f32_e32 v13, 0x3e0293ee, v13
	v_cmp_le_i32_e32 vcc, v40, v127
	v_or_b32_e32 v40, 20, v41
	v_max3_f32 v39, v39, v6, v7
	v_cndmask_b32_e32 v13, v210, v13, vcc
	v_mul_f32_e32 v14, 0x3e0293ee, v14
	v_cmp_le_i32_e32 vcc, v40, v127
	v_or_b32_e32 v40, 21, v41
	v_max3_f32 v39, v39, v8, v9
	v_cndmask_b32_e32 v14, v210, v14, vcc
	v_mul_f32_e32 v15, 0x3e0293ee, v15
	v_cmp_le_i32_e32 vcc, v40, v127
	v_or_b32_e32 v40, 22, v41
	v_max3_f32 v39, v39, v10, v11
	v_cndmask_b32_e32 v15, v210, v15, vcc
	v_mul_f32_e32 v16, 0x3e0293ee, v16
	v_cmp_le_i32_e32 vcc, v40, v127
	v_or_b32_e32 v40, 23, v41
	v_max3_f32 v39, v39, v12, v13
	v_cndmask_b32_e32 v16, v210, v16, vcc
	v_mul_f32_e32 v17, 0x3e0293ee, v17
	v_cmp_le_i32_e32 vcc, v40, v127
	v_max3_f32 v39, v39, v14, v15
	s_nop 0
	v_cndmask_b32_e32 v17, v210, v17, vcc
	v_cmp_lt_i32_e32 vcc, v203, v202
	v_max3_f32 v40, v39, v16, v17
	s_nop 0
	v_cndmask_b32_e32 v39, v200, v203, vcc
	v_lshlrev_b32_e32 v39, 2, v39
	ds_bpermute_b32 v42, v39, v40
	s_waitcnt lgkmcnt(0)
	v_max_f32_e32 v42, v42, v42
	v_max_f32_e32 v40, v40, v42
	v_add_f32_e32 v42, 0x41000000, v141
	v_cmp_le_f32_e32 vcc, v40, v42
	v_max_f32_e32 v42, v141, v141
	s_cmp_eq_u64 vcc, exec
	v_max_f32_e32 v40, v42, v40
	s_cselect_b64 vcc, -1, 0
	v_sub_f32_e32 v42, v141, v40
	v_exp_f32_e32 v48, v42
	v_cndmask_b32_e32 v42, v40, v141, vcc
	v_sub_f32_e32 v2, v2, v42
	v_exp_f32_e32 v2, v2
	v_sub_f32_e32 v3, v3, v42
	v_exp_f32_e32 v3, v3
	v_cndmask_b32_e64 v48, v48, 1.0, vcc
	v_add_f32_e32 v2, 0, v2
	v_add_f32_e32 v2, v3, v2
	v_sub_f32_e32 v3, v4, v42
	v_exp_f32_e32 v3, v3
	s_nop 0
	v_add_f32_e32 v2, v3, v2
	v_sub_f32_e32 v3, v5, v42
	v_exp_f32_e32 v3, v3
	s_nop 0
	v_add_f32_e32 v2, v3, v2
	v_sub_f32_e32 v3, v6, v42
	v_exp_f32_e32 v3, v3
	s_nop 0
	v_add_f32_e32 v2, v3, v2
	v_sub_f32_e32 v3, v7, v42
	v_exp_f32_e32 v3, v3
	s_nop 0
	v_add_f32_e32 v2, v3, v2
	v_sub_f32_e32 v3, v8, v42
	v_exp_f32_e32 v3, v3
	s_nop 0
	v_add_f32_e32 v2, v3, v2
	v_sub_f32_e32 v3, v9, v42
	v_exp_f32_e32 v3, v3
	s_nop 0
	v_add_f32_e32 v2, v3, v2
	v_sub_f32_e32 v3, v10, v42
	v_exp_f32_e32 v3, v3
	s_nop 0
	v_add_f32_e32 v2, v3, v2
	v_sub_f32_e32 v3, v11, v42
	v_exp_f32_e32 v3, v3
	s_nop 0
	v_add_f32_e32 v2, v3, v2
	v_sub_f32_e32 v3, v12, v42
	v_exp_f32_e32 v3, v3
	s_nop 0
	v_add_f32_e32 v2, v3, v2
	v_sub_f32_e32 v3, v13, v42
	v_exp_f32_e32 v3, v3
	s_nop 0
	v_add_f32_e32 v2, v3, v2
	v_sub_f32_e32 v3, v14, v42
	v_exp_f32_e32 v3, v3
	s_nop 0
	v_add_f32_e32 v2, v3, v2
	v_sub_f32_e32 v3, v15, v42
	v_exp_f32_e32 v3, v3
	s_nop 0
	v_add_f32_e32 v2, v3, v2
	v_sub_f32_e32 v3, v16, v42
	v_exp_f32_e32 v3, v3
	s_nop 0
	v_add_f32_e32 v2, v3, v2
	v_sub_f32_e32 v3, v17, v42
	v_exp_f32_e32 v3, v3
	s_nop 0
	v_add_f32_e32 v2, v3, v2
	ds_bpermute_b32 v3, v39, v2
	s_waitcnt lgkmcnt(0)
; template <int MODE, int DQK>
; DEV void flash_half(FlashState& s, f32x16* imp, const bf16x8* qf, const char* st, int kh, int kb, int qpos, float cq,
;                     const float* __restrict__ cumk, bool selbit, float c2, float invl, int r32, int hh, int wqmin_, int wqmax_) {
;   f32x16 S = zero16();
;   const int pr32 = pi32(r32);
;   const char* kp = st + (kh * 32 + pr32) * (DQK * 2);
;   const int kkey = (DQK == 128) ? (pr32 & 15) : ((pr32 >> 1) & 7);
; #pragma unroll
;   for (int ks = 0; ks < DQK / 16; ++ks) { bf16x8 kf = *(const bf16x8*)(kp + (((ks * 2 + hh) ^ kkey) << 4)); S = mfma(kf, qf[ks], S); }
;   const int kbase = kb + 8 * hh;
;   float pr[16];
;   if (MODE == M_SB) {
;     float lk[16];
;     float Tlo = 0.f, Thi = 0.f;
; #pragma unroll
;     for (int r = 0; r < 16; ++r) {
;       int key = kbase + r + (r >= 8 ? 8 : 0);
;       float z2 = S[r] * c2;
;       float sp2 = fmaxf(z2, 0.f) + lg2(1.f + ex2(-fabsf(z2)));
;       lk[r] = (key < qpos) ? -sp2 : 0.f;
;       if (r < 8) Tlo += lk[r]; else Thi += lk[r];
;     }
;     float Plo = __shfl_xor(Tlo, 32), Phi = __shfl_xor(Thi, 32);
;     float baseLo = s.R + Thi + Phi + (hh == 0 ? Plo : 0.f);
;     float baseHi = s.R + (hh == 0 ? Phi : 0.f);
;     float run = 0.f;
; #pragma unroll
;     for (int r = 7; r >= 0; --r) { pr[r] = (kbase + r < qpos) ? ex2(S[r] * c2 + lk[r] + baseLo + run) : 0.f; run += lk[r]; }
;     run = 0.f;
; #pragma unroll
;     for (int r = 15; r >= 8; --r) { pr[r] = (kbase + r + 8 < qpos) ? ex2(S[r] * c2 + lk[r] + baseHi + run) : 0.f; run += lk[r]; }
;     s.R += Tlo + Thi + Plo + Phi;
;   } else {
;     float t[16];
;     float ck[16];
;     if (MODE == M_FOX) {
;       const float* cl = (const float*)(st + 32768) + kh * 32 + 8 * hh;
;       float4 a0 = *(const float4*)(cl), a1 = *(const float4*)(cl + 4);
;       float4 a2 = *(const float4*)(cl + 16), a3 = *(const float4*)(cl + 20);
;       ck[0] = a0.x; ck[1] = a0.y; ck[2] = a0.z; ck[3] = a0.w; ck[4] = a1.x; ck[5] = a1.y; ck[6] = a1.z; ck[7] = a1.w;
;       ck[8] = a2.x; ck[9] = a2.y; ck[10] = a2.z; ck[11] = a2.w; ck[12] = a3.x; ck[13] = a3.y; ck[14] = a3.z; ck[15] = a3.w;
;     }
;     float tmax = -__builtin_inff();
;     bool nomask = (kb + 31 <= wqmin_);
;     if (MODE == M_WIN) nomask = nomask && (kb > wqmax_ - 512);
;     if (MODE == M_SLC) nomask = nomask && __all(selbit);
	v_add_f32_e32 v40, v2, v3
	ds_read_b128 v[2:5], v46 offset:8192
	v_fmac_f32_e32 v40, v47, v48
	ds_read_b128 v[46:49], v45 offset:8192
	s_waitcnt lgkmcnt(1)
	v_mfma_f32_32x32x16_bf16 v[2:17], v[2:5], v[82:85], 0
	s_waitcnt lgkmcnt(0)
	v_mfma_f32_32x32x16_bf16 v[2:17], v[46:49], v[86:89], v[2:17]
	ds_read_b128 v[44:47], v44 offset:8192
	s_waitcnt lgkmcnt(0)
	v_mfma_f32_32x32x16_bf16 v[2:17], v[44:47], v[90:93], v[2:17]
	ds_read_b128 v[44:47], v43 offset:8192
	s_waitcnt lgkmcnt(0)
	v_mfma_f32_32x32x16_bf16 v[2:17], v[44:47], v[94:97], v[2:17]
	ds_read_b128 v[44:47], v21 offset:8192
	s_waitcnt lgkmcnt(0)
	v_mfma_f32_32x32x16_bf16 v[2:17], v[44:47], v[98:101], v[2:17]
	ds_read_b128 v[44:47], v20 offset:8192
	s_waitcnt lgkmcnt(0)
	v_mfma_f32_32x32x16_bf16 v[2:17], v[44:47], v[102:105], v[2:17]
	ds_read_b128 v[44:47], v19 offset:8192
	ds_read_b128 v[18:21], v18 offset:8192
	s_waitcnt lgkmcnt(1)
	v_mfma_f32_32x32x16_bf16 v[2:17], v[44:47], v[106:109], v[2:17]
	s_waitcnt lgkmcnt(0)
	v_mfma_f32_32x32x16_bf16 v[2:17], v[18:21], v[110:113], v[2:17]
	v_or_b32_e32 v18, 32, v41
	v_cmp_le_i32_e32 vcc, v18, v127
	v_or_b32_e32 v19, 34, v41
	s_nop 8
	v_mul_f32_e32 v2, 0x3e0293ee, v2
	v_cndmask_b32_e32 v2, v210, v2, vcc
	v_cmp_lt_i32_e32 vcc, v18, v127
	v_mul_f32_e32 v3, 0x3e0293ee, v3
	v_mul_f32_e32 v4, 0x3e0293ee, v4
	v_cndmask_b32_e32 v3, v210, v3, vcc
	v_cmp_le_i32_e32 vcc, v19, v127
	v_or_b32_e32 v19, 35, v41
	v_mul_f32_e32 v5, 0x3e0293ee, v5
	v_cndmask_b32_e32 v4, v210, v4, vcc
	v_cmp_le_i32_e32 vcc, v19, v127
	v_or_b32_e32 v19, 36, v41
	v_mul_f32_e32 v6, 0x3e0293ee, v6
	v_cndmask_b32_e32 v5, v210, v5, vcc
	v_cmp_le_i32_e32 vcc, v19, v127
	v_or_b32_e32 v19, 37, v41
	v_mul_f32_e32 v7, 0x3e0293ee, v7
	v_cndmask_b32_e32 v6, v210, v6, vcc
	v_cmp_le_i32_e32 vcc, v19, v127
	v_or_b32_e32 v19, 38, v41
	v_mul_f32_e32 v8, 0x3e0293ee, v8
	v_cndmask_b32_e32 v7, v210, v7, vcc
	v_cmp_le_i32_e32 vcc, v19, v127
	v_or_b32_e32 v19, 39, v41
	v_mul_f32_e32 v9, 0x3e0293ee, v9
	v_cndmask_b32_e32 v8, v210, v8, vcc
	v_cmp_le_i32_e32 vcc, v19, v127
	v_or_b32_e32 v19, 48, v41
	v_mul_f32_e32 v10, 0x3e0293ee, v10
	v_cndmask_b32_e32 v9, v210, v9, vcc
	v_cmp_le_i32_e32 vcc, v19, v127
	v_or_b32_e32 v19, 49, v41
	v_mul_f32_e32 v11, 0x3e0293ee, v11
	v_cndmask_b32_e32 v10, v210, v10, vcc
	v_cmp_le_i32_e32 vcc, v19, v127
	v_or_b32_e32 v19, 50, v41
	v_max3_f32 v18, v2, s89, v3
	v_cndmask_b32_e32 v11, v210, v11, vcc
	v_mul_f32_e32 v12, 0x3e0293ee, v12
	v_cmp_le_i32_e32 vcc, v19, v127
	v_or_b32_e32 v19, 51, v41
	v_max3_f32 v18, v18, v4, v5
	v_cndmask_b32_e32 v12, v210, v12, vcc
	v_mul_f32_e32 v13, 0x3e0293ee, v13
	v_cmp_le_i32_e32 vcc, v19, v127
	v_or_b32_e32 v19, 52, v41
	v_max3_f32 v18, v18, v6, v7
	v_cndmask_b32_e32 v13, v210, v13, vcc
	v_mul_f32_e32 v14, 0x3e0293ee, v14
	v_cmp_le_i32_e32 vcc, v19, v127
	v_or_b32_e32 v19, 53, v41
	v_max3_f32 v18, v18, v8, v9
	v_cndmask_b32_e32 v14, v210, v14, vcc
	v_mul_f32_e32 v15, 0x3e0293ee, v15
	v_cmp_le_i32_e32 vcc, v19, v127
	v_or_b32_e32 v19, 54, v41
	v_max3_f32 v18, v18, v10, v11
	v_cndmask_b32_e32 v15, v210, v15, vcc
	v_mul_f32_e32 v16, 0x3e0293ee, v16
	v_cmp_le_i32_e32 vcc, v19, v127
	v_or_b32_e32 v19, 55, v41
	v_max3_f32 v18, v18, v12, v13
	v_cndmask_b32_e32 v16, v210, v16, vcc
	v_mul_f32_e32 v17, 0x3e0293ee, v17
	v_cmp_le_i32_e32 vcc, v19, v127
	v_max3_f32 v18, v18, v14, v15
	s_nop 0
	v_cndmask_b32_e32 v17, v210, v17, vcc
	v_max3_f32 v18, v18, v16, v17
	ds_bpermute_b32 v19, v39, v18
	s_waitcnt lgkmcnt(0)
	v_max_f32_e32 v19, v19, v19
	v_max_f32_e32 v18, v18, v19
	v_add_f32_e32 v19, 0x41000000, v42
	v_cmp_le_f32_e32 vcc, v18, v19
	s_cmp_eq_u64 vcc, exec
	v_max_f32_e32 v19, v42, v42
	s_cselect_b64 vcc, -1, 0
	v_max_f32_e32 v18, v19, v18
	v_cndmask_b32_e32 v141, v18, v42, vcc
	v_sub_f32_e32 v2, v2, v141
	v_exp_f32_e32 v2, v2
	v_sub_f32_e32 v3, v3, v141
	v_exp_f32_e32 v3, v3
	v_sub_f32_e32 v19, v42, v18
	v_add_f32_e32 v2, 0, v2
	v_exp_f32_e32 v19, v19
	v_add_f32_e32 v2, v3, v2
	v_sub_f32_e32 v3, v4, v141
	v_exp_f32_e32 v3, v3
	v_cndmask_b32_e64 v18, v19, 1.0, vcc
	v_add_f32_e32 v2, v3, v2
	v_sub_f32_e32 v3, v5, v141
	v_exp_f32_e32 v3, v3
	s_nop 0
	v_add_f32_e32 v2, v3, v2
	v_sub_f32_e32 v3, v6, v141
	v_exp_f32_e32 v3, v3
	s_nop 0
	v_add_f32_e32 v2, v3, v2
	v_sub_f32_e32 v3, v7, v141
	v_exp_f32_e32 v3, v3
	s_nop 0
	v_add_f32_e32 v2, v3, v2
	v_sub_f32_e32 v3, v8, v141
	v_exp_f32_e32 v3, v3
	s_nop 0
	v_add_f32_e32 v2, v3, v2
	v_sub_f32_e32 v3, v9, v141
	v_exp_f32_e32 v3, v3
	s_nop 0
	v_add_f32_e32 v2, v3, v2
	v_sub_f32_e32 v3, v10, v141
	v_exp_f32_e32 v3, v3
	s_nop 0
	v_add_f32_e32 v2, v3, v2
	v_sub_f32_e32 v3, v11, v141
	v_exp_f32_e32 v3, v3
	s_nop 0
	v_add_f32_e32 v2, v3, v2
	v_sub_f32_e32 v3, v12, v141
	v_exp_f32_e32 v3, v3
	s_nop 0
	v_add_f32_e32 v2, v3, v2
	v_sub_f32_e32 v3, v13, v141
	v_exp_f32_e32 v3, v3
	s_nop 0
	v_add_f32_e32 v2, v3, v2
	v_sub_f32_e32 v3, v14, v141
	v_exp_f32_e32 v3, v3
	s_nop 0
	v_add_f32_e32 v2, v3, v2
	v_sub_f32_e32 v3, v15, v141
	v_exp_f32_e32 v3, v3
	s_nop 0
	v_add_f32_e32 v2, v3, v2
	v_sub_f32_e32 v3, v16, v141
	v_exp_f32_e32 v3, v3
	s_nop 0
	v_add_f32_e32 v2, v3, v2
	v_sub_f32_e32 v3, v17, v141
	v_exp_f32_e32 v3, v3
	s_nop 0
	v_add_f32_e32 v2, v3, v2
	ds_bpermute_b32 v3, v39, v2
	s_waitcnt lgkmcnt(0)
	v_add_f32_e32 v47, v2, v3
	v_fmac_f32_e32 v47, v40, v18

.LBB0_206:
	s_lshl_b32 s6, s6, 6
	v_cmp_le_i32_e32 vcc, s6, v133
	s_and_saveexec_b64 s[12:13], vcc
	s_cbranch_execz .LBB0_208
	s_mul_i32 s7, s19, 0x8100
	v_add_u32_e32 v1, s7, v156
	v_add_u32_e32 v175, v1, v157
	ds_read_b128 v[66:69], v175
	v_add_u32_e32 v174, v1, v158
	ds_read_b128 v[114:117], v174
	v_add_u32_e32 v173, v1, v159
	v_add_u32_e32 v172, v1, v160
	v_or_b32_e32 v171, s6, v165
	v_cmp_le_i32_e32 vcc, v171, v127
	s_waitcnt lgkmcnt(0)
	v_mfma_f32_32x32x16_bf16 v[66:81], v[66:69], v[82:85], 0
	v_mfma_f32_32x32x16_bf16 v[66:81], v[114:117], v[86:89], v[66:81]
	ds_read_b128 v[114:117], v173
	s_waitcnt lgkmcnt(0)
	v_mfma_f32_32x32x16_bf16 v[66:81], v[114:117], v[90:93], v[66:81]
	ds_read_b128 v[114:117], v172
	s_waitcnt lgkmcnt(0)
	v_mfma_f32_32x32x16_bf16 v[66:81], v[114:117], v[94:97], v[66:81]
	v_add_u32_e32 v117, v1, v161
	ds_read_b128 v[176:179], v117
	v_add_u32_e32 v116, v1, v162
	v_add_u32_e32 v115, v1, v163
	v_add_u32_e32 v114, v1, v164
	s_waitcnt lgkmcnt(0)
	v_mfma_f32_32x32x16_bf16 v[66:81], v[176:179], v[98:101], v[66:81]
	ds_read_b128 v[176:179], v116
	s_waitcnt lgkmcnt(0)
	v_mfma_f32_32x32x16_bf16 v[66:81], v[176:179], v[102:105], v[66:81]
	ds_read_b128 v[176:179], v115
	s_waitcnt lgkmcnt(0)
	v_mfma_f32_32x32x16_bf16 v[66:81], v[176:179], v[106:109], v[66:81]
	ds_read_b128 v[176:179], v114
	s_waitcnt lgkmcnt(0)
	v_mfma_f32_32x32x16_bf16 v[66:81], v[176:179], v[110:113], v[66:81]
	s_nop 11
	v_mul_f32_e32 v1, 0x3e0293ee, v66
	v_cndmask_b32_e32 v1, v210, v1, vcc
	v_cmp_lt_i32_e32 vcc, v171, v127
	v_mul_f32_e32 v66, 0x3e0293ee, v67
	v_or_b32_e32 v67, 2, v171
	v_cndmask_b32_e32 v66, v210, v66, vcc
	v_mul_f32_e32 v68, 0x3e0293ee, v68
	v_cmp_le_i32_e32 vcc, v67, v127
	v_mul_f32_e32 v69, 0x3e0293ee, v69
	v_mul_f32_e32 v70, 0x3e0293ee, v70
	v_cndmask_b32_e32 v67, v210, v68, vcc
	v_or_b32_e32 v68, 3, v171
	v_cmp_le_i32_e32 vcc, v68, v127
	v_mul_f32_e32 v71, 0x3e0293ee, v71
	v_mul_f32_e32 v72, 0x3e0293ee, v72
	v_cndmask_b32_e32 v68, v210, v69, vcc
	v_or_b32_e32 v69, 4, v171
	v_cmp_le_i32_e32 vcc, v69, v127
	v_mul_f32_e32 v73, 0x3e0293ee, v73
	v_mul_f32_e32 v74, 0x3e0293ee, v74
	v_cndmask_b32_e32 v69, v210, v70, vcc
	v_or_b32_e32 v70, 5, v171
	v_cmp_le_i32_e32 vcc, v70, v127
	v_mul_f32_e32 v75, 0x3e0293ee, v75
	v_mul_f32_e32 v76, 0x3e0293ee, v76
	v_cndmask_b32_e32 v70, v210, v71, vcc
	v_or_b32_e32 v71, 6, v171
	v_cmp_le_i32_e32 vcc, v71, v127
	v_mul_f32_e32 v77, 0x3e0293ee, v77
	v_mul_f32_e32 v78, 0x3e0293ee, v78
	v_cndmask_b32_e32 v71, v210, v72, vcc
	v_or_b32_e32 v72, 7, v171
	v_cmp_le_i32_e32 vcc, v72, v127
	v_mul_f32_e32 v79, 0x3e0293ee, v79
	v_sub_f32_e32 v1, v1, v141
	v_cndmask_b32_e32 v72, v210, v73, vcc
	v_or_b32_e32 v73, 16, v171
	v_cmp_le_i32_e32 vcc, v73, v127
	v_sub_f32_e32 v66, v66, v141
	v_exp_f32_e32 v1, v1
	v_cndmask_b32_e32 v73, v210, v74, vcc
	v_or_b32_e32 v74, 17, v171
	v_cmp_le_i32_e32 vcc, v74, v127
	v_exp_f32_e32 v66, v66
	v_sub_f32_e32 v67, v67, v141
	v_cndmask_b32_e32 v74, v210, v75, vcc
	v_or_b32_e32 v75, 18, v171
	v_cmp_le_i32_e32 vcc, v75, v127
	v_sub_f32_e32 v68, v68, v141
	v_sub_f32_e32 v69, v69, v141
	v_cndmask_b32_e32 v75, v210, v76, vcc
	v_or_b32_e32 v76, 19, v171
	v_cmp_le_i32_e32 vcc, v76, v127
	v_sub_f32_e32 v72, v72, v141
	v_exp_f32_e32 v67, v67
	v_cndmask_b32_e32 v76, v210, v77, vcc
	v_or_b32_e32 v77, 20, v171
	v_cmp_le_i32_e32 vcc, v77, v127
	v_exp_f32_e32 v68, v68
	v_exp_f32_e32 v69, v69
	v_cndmask_b32_e32 v77, v210, v78, vcc
	v_or_b32_e32 v78, 21, v171
	v_cmp_le_i32_e32 vcc, v78, v127
	v_sub_f32_e32 v70, v70, v141
	v_sub_f32_e32 v71, v71, v141
	v_cndmask_b32_e32 v78, v210, v79, vcc
	v_sub_f32_e32 v78, v78, v141
	v_exp_f32_e32 v72, v72
	v_sub_f32_e32 v74, v74, v141
	v_sub_f32_e32 v75, v75, v141
	v_sub_f32_e32 v76, v76, v141
	v_sub_f32_e32 v77, v77, v141
	v_exp_f32_e32 v78, v78
	v_exp_f32_e32 v70, v70
	v_exp_f32_e32 v71, v71
	v_sub_f32_e32 v73, v73, v141
	v_exp_f32_e32 v74, v74
	v_exp_f32_e32 v75, v75
	v_exp_f32_e32 v76, v76
	v_exp_f32_e32 v77, v77
	v_exp_f32_e32 v73, v73
	v_mul_f32_e32 v1, v143, v1
	v_mul_f32_e32 v66, v143, v66
	v_or_b32_e32 v79, 22, v171
	v_mul_f32_e32 v67, v143, v67
	v_mul_f32_e32 v68, v143, v68
	v_mul_f32_e32 v69, v143, v69
	v_mul_f32_e32 v72, v143, v72
	v_mul_f32_e32 v78, v143, v78
	v_cvt_pk_bf16_f32 v66, v1, v66
	v_add_u32_e32 v1, s7, v166
	v_mul_f32_e32 v80, 0x3e0293ee, v80
	v_cmp_le_i32_e32 vcc, v79, v127
	v_mul_f32_e32 v70, v143, v70
	v_mul_f32_e32 v71, v143, v71
	v_mul_f32_e32 v74, v143, v74
	v_mul_f32_e32 v75, v143, v75
	v_mul_f32_e32 v76, v143, v76
	v_mul_f32_e32 v77, v143, v77
	v_cvt_pk_bf16_f32 v67, v67, v68
	v_cvt_pk_bf16_f32 v68, v69, v70
	v_cvt_pk_bf16_f32 v69, v71, v72
	v_cvt_pk_bf16_f32 v72, v77, v78
	v_add_u32_e32 v78, v1, v167
	v_cndmask_b32_e32 v79, v210, v80, vcc
	v_or_b32_e32 v80, 23, v171
	v_mul_f32_e32 v73, v143, v73
	v_cvt_pk_bf16_f32 v70, v73, v74
	v_cvt_pk_bf16_f32 v71, v75, v76
	ds_read_b128 v[74:77], v78 offset:16384
	v_mul_f32_e32 v81, 0x3e0293ee, v81
	v_cmp_le_i32_e32 vcc, v80, v127
	v_sub_f32_e32 v79, v79, v141
	v_exp_f32_e32 v79, v79
	v_cndmask_b32_e32 v80, v210, v81, vcc
	v_sub_f32_e32 v80, v80, v141
	v_exp_f32_e32 v80, v80
	v_mul_f32_e32 v79, v143, v79
	s_waitcnt lgkmcnt(0)
	v_mfma_f32_32x32x16_bf16 v[50:65], v[74:77], v[66:69], v[50:65]
	v_mul_f32_e32 v80, v143, v80
	v_cvt_pk_bf16_f32 v73, v79, v80
	v_add_u32_e32 v79, v1, v168
	ds_read_b128 v[74:77], v79 offset:16384
	s_waitcnt lgkmcnt(0)
	v_mfma_f32_32x32x16_bf16 v[50:65], v[74:77], v[70:73], v[50:65]
	ds_read_b128 v[74:77], v78 offset:20480
	s_waitcnt lgkmcnt(0)
	v_mfma_f32_32x32x16_bf16 v[34:49], v[74:77], v[66:69], v[34:49]
	ds_read_b128 v[74:77], v79 offset:20480
	s_waitcnt lgkmcnt(0)
	v_mfma_f32_32x32x16_bf16 v[34:49], v[74:77], v[70:73], v[34:49]
	ds_read_b128 v[74:77], v78 offset:24576
	s_waitcnt lgkmcnt(0)
	v_mfma_f32_32x32x16_bf16 v[18:33], v[74:77], v[66:69], v[18:33]
	ds_read_b128 v[74:77], v79 offset:24576
	s_waitcnt lgkmcnt(0)
	v_mfma_f32_32x32x16_bf16 v[18:33], v[74:77], v[70:73], v[18:33]
	ds_read_b128 v[74:77], v78 offset:28672
	s_waitcnt lgkmcnt(0)
	v_mfma_f32_32x32x16_bf16 v[2:17], v[74:77], v[66:69], v[2:17]
	ds_read_b128 v[66:69], v79 offset:28672
	s_waitcnt lgkmcnt(0)
	v_mfma_f32_32x32x16_bf16 v[2:17], v[66:69], v[70:73], v[2:17]
	ds_read_b128 v[66:69], v175 offset:8192
	ds_read_b128 v[174:177], v174 offset:8192
	s_waitcnt lgkmcnt(1)
	v_mfma_f32_32x32x16_bf16 v[66:81], v[66:69], v[82:85], 0
	s_waitcnt lgkmcnt(0)
	v_mfma_f32_32x32x16_bf16 v[66:81], v[174:177], v[86:89], v[66:81]
	ds_read_b128 v[174:177], v173 offset:8192
	s_waitcnt lgkmcnt(0)
	v_mfma_f32_32x32x16_bf16 v[66:81], v[174:177], v[90:93], v[66:81]
	ds_read_b128 v[172:175], v172 offset:8192
	s_waitcnt lgkmcnt(0)
	v_mfma_f32_32x32x16_bf16 v[66:81], v[172:175], v[94:97], v[66:81]
	ds_read_b128 v[172:175], v117 offset:8192
	s_waitcnt lgkmcnt(0)
	v_mfma_f32_32x32x16_bf16 v[66:81], v[172:175], v[98:101], v[66:81]
	ds_read_b128 v[172:175], v116 offset:8192
	s_waitcnt lgkmcnt(0)
	v_mfma_f32_32x32x16_bf16 v[66:81], v[172:175], v[102:105], v[66:81]
	ds_read_b128 v[172:175], v115 offset:8192
	ds_read_b128 v[114:117], v114 offset:8192
	s_waitcnt lgkmcnt(1)
	v_mfma_f32_32x32x16_bf16 v[66:81], v[172:175], v[106:109], v[66:81]
	s_waitcnt lgkmcnt(0)
	v_mfma_f32_32x32x16_bf16 v[66:81], v[114:117], v[110:113], v[66:81]
	v_or_b32_e32 v114, 32, v171
	v_cmp_le_i32_e32 vcc, v114, v127
	s_nop 9
	v_mul_f32_e32 v66, 0x3e0293ee, v66
	v_cndmask_b32_e32 v66, v210, v66, vcc
	v_cmp_lt_i32_e32 vcc, v114, v127
	v_mul_f32_e32 v67, 0x3e0293ee, v67
	v_or_b32_e32 v114, 34, v171
	v_cndmask_b32_e32 v67, v210, v67, vcc
	v_mul_f32_e32 v68, 0x3e0293ee, v68
	v_cmp_le_i32_e32 vcc, v114, v127
	v_or_b32_e32 v114, 35, v171
	v_mul_f32_e32 v69, 0x3e0293ee, v69
	v_cndmask_b32_e32 v68, v210, v68, vcc
	v_cmp_le_i32_e32 vcc, v114, v127
	v_or_b32_e32 v114, 36, v171
	v_mul_f32_e32 v70, 0x3e0293ee, v70
	v_cndmask_b32_e32 v69, v210, v69, vcc
	v_cmp_le_i32_e32 vcc, v114, v127
	v_or_b32_e32 v114, 37, v171
	v_mul_f32_e32 v71, 0x3e0293ee, v71
	v_cndmask_b32_e32 v70, v210, v70, vcc
	v_cmp_le_i32_e32 vcc, v114, v127
	v_or_b32_e32 v114, 38, v171
	v_mul_f32_e32 v72, 0x3e0293ee, v72
	v_cndmask_b32_e32 v71, v210, v71, vcc
	v_cmp_le_i32_e32 vcc, v114, v127
	v_or_b32_e32 v114, 39, v171
	v_mul_f32_e32 v73, 0x3e0293ee, v73
	v_cndmask_b32_e32 v72, v210, v72, vcc
	v_cmp_le_i32_e32 vcc, v114, v127
	v_or_b32_e32 v114, 48, v171
	v_mul_f32_e32 v74, 0x3e0293ee, v74
	v_cndmask_b32_e32 v73, v210, v73, vcc
	v_cmp_le_i32_e32 vcc, v114, v127
	v_or_b32_e32 v114, 49, v171
	v_mul_f32_e32 v75, 0x3e0293ee, v75
	v_cndmask_b32_e32 v74, v210, v74, vcc
	v_cmp_le_i32_e32 vcc, v114, v127
	v_or_b32_e32 v114, 50, v171
	v_mul_f32_e32 v76, 0x3e0293ee, v76
	v_cndmask_b32_e32 v75, v210, v75, vcc
	v_cmp_le_i32_e32 vcc, v114, v127
	v_or_b32_e32 v114, 51, v171
	v_mul_f32_e32 v77, 0x3e0293ee, v77
	v_cndmask_b32_e32 v76, v210, v76, vcc
	v_cmp_le_i32_e32 vcc, v114, v127
	v_or_b32_e32 v114, 52, v171
	v_mul_f32_e32 v78, 0x3e0293ee, v78
	v_cndmask_b32_e32 v77, v210, v77, vcc
	v_cmp_le_i32_e32 vcc, v114, v127
	v_or_b32_e32 v114, 53, v171
	v_mul_f32_e32 v79, 0x3e0293ee, v79
	v_cndmask_b32_e32 v78, v210, v78, vcc
	v_cmp_le_i32_e32 vcc, v114, v127
	v_sub_f32_e32 v66, v66, v141
	v_sub_f32_e32 v67, v67, v141
	v_cndmask_b32_e32 v79, v210, v79, vcc
	v_sub_f32_e32 v69, v69, v141
	v_sub_f32_e32 v72, v72, v141
	v_sub_f32_e32 v78, v78, v141
	v_exp_f32_e32 v66, v66
	v_exp_f32_e32 v67, v67
	v_sub_f32_e32 v68, v68, v141
	v_exp_f32_e32 v69, v69
	v_sub_f32_e32 v70, v70, v141
	v_sub_f32_e32 v71, v71, v141
	v_exp_f32_e32 v72, v72
	v_sub_f32_e32 v73, v73, v141
	v_sub_f32_e32 v74, v74, v141
	v_sub_f32_e32 v75, v75, v141
	v_sub_f32_e32 v76, v76, v141
	v_sub_f32_e32 v77, v77, v141
	v_exp_f32_e32 v78, v78
	v_sub_f32_e32 v79, v79, v141
	v_exp_f32_e32 v68, v68
	v_exp_f32_e32 v70, v70
	v_exp_f32_e32 v71, v71
	v_exp_f32_e32 v73, v73
	v_exp_f32_e32 v74, v74
	v_exp_f32_e32 v75, v75
	v_exp_f32_e32 v76, v76
	v_exp_f32_e32 v77, v77
	v_exp_f32_e32 v79, v79
	v_mul_f32_e32 v66, v143, v66
	v_mul_f32_e32 v67, v143, v67
	v_mul_f32_e32 v69, v143, v69
	v_mul_f32_e32 v72, v143, v72
	v_mul_f32_e32 v78, v143, v78
	v_mul_f32_e32 v68, v143, v68
	v_mul_f32_e32 v70, v143, v70
	v_mul_f32_e32 v71, v143, v71
	v_mul_f32_e32 v73, v143, v73
	v_mul_f32_e32 v74, v143, v74
	v_mul_f32_e32 v75, v143, v75
	v_mul_f32_e32 v76, v143, v76
	v_mul_f32_e32 v77, v143, v77
	v_mul_f32_e32 v79, v143, v79
	v_cvt_pk_bf16_f32 v66, v66, v67
	v_cvt_pk_bf16_f32 v67, v68, v69
	v_cvt_pk_bf16_f32 v69, v72, v73
	v_cvt_pk_bf16_f32 v72, v78, v79
	v_add_u32_e32 v78, v1, v169
	v_cvt_pk_bf16_f32 v68, v70, v71
	v_cvt_pk_bf16_f32 v70, v74, v75
	v_cvt_pk_bf16_f32 v71, v76, v77
	ds_read_b128 v[74:77], v78 offset:16384
	v_add_u32_e32 v1, v1, v170
	v_or_b32_e32 v114, 54, v171
	s_waitcnt lgkmcnt(0)
	v_mfma_f32_32x32x16_bf16 v[50:65], v[74:77], v[66:69], v[50:65]
	ds_read_b128 v[74:77], v1 offset:16384
	v_mul_f32_e32 v80, 0x3e0293ee, v80
	v_cmp_le_i32_e32 vcc, v114, v127
	v_or_b32_e32 v114, 55, v171
	v_mul_f32_e32 v81, 0x3e0293ee, v81
	v_cndmask_b32_e32 v80, v210, v80, vcc
	v_cmp_le_i32_e32 vcc, v114, v127
	v_sub_f32_e32 v80, v80, v141
	v_exp_f32_e32 v80, v80
	v_cndmask_b32_e32 v81, v210, v81, vcc
	v_sub_f32_e32 v81, v81, v141
	v_exp_f32_e32 v81, v81
	v_mul_f32_e32 v80, v143, v80
	v_mul_f32_e32 v81, v143, v81
	v_cvt_pk_bf16_f32 v73, v80, v81
	s_waitcnt lgkmcnt(0)
	v_mfma_f32_32x32x16_bf16 v[50:65], v[74:77], v[70:73], v[50:65]
	ds_read_b128 v[74:77], v78 offset:20480
	s_waitcnt lgkmcnt(0)
	v_mfma_f32_32x32x16_bf16 v[34:49], v[74:77], v[66:69], v[34:49]
	ds_read_b128 v[74:77], v1 offset:20480
	s_waitcnt lgkmcnt(0)
	v_mfma_f32_32x32x16_bf16 v[34:49], v[74:77], v[70:73], v[34:49]
	ds_read_b128 v[74:77], v78 offset:24576
	s_waitcnt lgkmcnt(0)
	v_mfma_f32_32x32x16_bf16 v[18:33], v[74:77], v[66:69], v[18:33]
	ds_read_b128 v[74:77], v1 offset:24576
	s_waitcnt lgkmcnt(0)
	v_mfma_f32_32x32x16_bf16 v[18:33], v[74:77], v[70:73], v[18:33]
	ds_read_b128 v[74:77], v78 offset:28672
	s_waitcnt lgkmcnt(0)
	v_mfma_f32_32x32x16_bf16 v[2:17], v[74:77], v[66:69], v[2:17]
	ds_read_b128 v[66:69], v1 offset:28672
	s_waitcnt lgkmcnt(0)
	v_mfma_f32_32x32x16_bf16 v[2:17], v[66:69], v[70:73], v[2:17]

; template <int MODE, int DQK>
; DEV void flash_half(FlashState& s, f32x16* imp, const bf16x8* qf, const char* st, int kh, int kb, int qpos, float cq,
;                     const float* __restrict__ cumk, bool selbit, float c2, float invl, int r32, int hh, int wqmin_, int wqmax_) {
;   f32x16 S = zero16();
;   const int pr32 = pi32(r32);
;   const char* kp = st + (kh * 32 + pr32) * (DQK * 2);
;   const int kkey = (DQK == 128) ? (pr32 & 15) : ((pr32 >> 1) & 7);
; #pragma unroll
;   for (int ks = 0; ks < DQK / 16; ++ks) { bf16x8 kf = *(const bf16x8*)(kp + (((ks * 2 + hh) ^ kkey) << 4)); S = mfma(kf, qf[ks], S); }
;   const int kbase = kb + 8 * hh;
;   float pr[16];
;   if (MODE == M_SB) {
;     float lk[16];
;     float Tlo = 0.f, Thi = 0.f;
; #pragma unroll
;     for (int r = 0; r < 16; ++r) {
;       int key = kbase + r + (r >= 8 ? 8 : 0);
;       float z2 = S[r] * c2;
;       float sp2 = fmaxf(z2, 0.f) + lg2(1.f + ex2(-fabsf(z2)));
;       lk[r] = (key < qpos) ? -sp2 : 0.f;
;       if (r < 8) Tlo += lk[r]; else Thi += lk[r];
;     }
;     float Plo = __shfl_xor(Tlo, 32), Phi = __shfl_xor(Thi, 32);
;     float baseLo = s.R + Thi + Phi + (hh == 0 ? Plo : 0.f);
;     float baseHi = s.R + (hh == 0 ? Phi : 0.f);
;     float run = 0.f;
; #pragma unroll
;     for (int r = 7; r >= 0; --r) { pr[r] = (kbase + r < qpos) ? ex2(S[r] * c2 + lk[r] + baseLo + run) : 0.f; run += lk[r]; }
;     run = 0.f;
; #pragma unroll
;     for (int r = 15; r >= 8; --r) { pr[r] = (kbase + r + 8 < qpos) ? ex2(S[r] * c2 + lk[r] + baseHi + run) : 0.f; run += lk[r]; }
;     s.R += Tlo + Thi + Plo + Phi;
;   } else {
;     float t[16];
;     float ck[16];
;     if (MODE == M_FOX) {
;       const float* cl = (const float*)(st + 32768) + kh * 32 + 8 * hh;
;       float4 a0 = *(const float4*)(cl), a1 = *(const float4*)(cl + 4);
;       float4 a2 = *(const float4*)(cl + 16), a3 = *(const float4*)(cl + 20);
;       ck[0] = a0.x; ck[1] = a0.y; ck[2] = a0.z; ck[3] = a0.w; ck[4] = a1.x; ck[5] = a1.y; ck[6] = a1.z; ck[7] = a1.w;
;       ck[8] = a2.x; ck[9] = a2.y; ck[10] = a2.z; ck[11] = a2.w; ck[12] = a3.x; ck[13] = a3.y; ck[14] = a3.z; ck[15] = a3.w;
;     }
;     float tmax = -__builtin_inff();
;     bool nomask = (kb + 31 <= wqmin_);
;     if (MODE == M_WIN) nomask = nomask && (kb > wqmax_ - 512);
;     if (MODE == M_SLC) nomask = nomask && __all(selbit);
.LBB0_277:
	s_lshl_b32 s18, s6, 6
	v_cmp_le_i32_e32 vcc, s18, v133
	s_and_saveexec_b64 s[14:15], vcc
	s_cbranch_execz .LBB0_298
	v_lshrrev_b64 v[2:3], s6, v[158:159]
	v_and_b32_e32 v1, 1, v2
	v_cmp_eq_u32_e64 s[8:9], 1, v1
	v_cmp_ne_u32_e32 vcc, 0, v1
	s_cbranch_vccz .LBB0_298
	s_mul_i32 s19, s31, 0x8100
	v_add_u32_e32 v1, s19, v164
	v_add_u32_e32 v184, v1, v165
	ds_read_b128 v[2:5], v184
	v_add_u32_e32 v163, v1, v166
	ds_read_b128 v[6:9], v163
	v_add_u32_e32 v185, v1, v168
	v_add_u32_e32 v186, v1, v169
	v_add_u32_e32 v187, v1, v170
	v_add_u32_e32 v188, v1, v171
	v_add_u32_e32 v189, v1, v172
	v_add_u32_e32 v190, v1, v173
	s_waitcnt lgkmcnt(0)
	v_mfma_f32_32x32x16_bf16 v[80:95], v[2:5], v[96:99], 0
	ds_read_b128 v[2:5], v185
	s_or_b32 s10, s18, 31
	v_cmp_gt_i32_e64 s[6:7], s10, v129
	v_cmp_le_i32_e32 vcc, s10, v129
	v_cndmask_b32_e64 v162, 0, 1, s[8:9]
	v_mfma_f32_32x32x16_bf16 v[80:95], v[6:9], v[100:103], v[80:95]
	ds_read_b128 v[6:9], v186
	s_waitcnt lgkmcnt(1)
	v_mfma_f32_32x32x16_bf16 v[80:95], v[2:5], v[104:107], v[80:95]
	ds_read_b128 v[2:5], v187
	s_waitcnt lgkmcnt(1)
	v_mfma_f32_32x32x16_bf16 v[80:95], v[6:9], v[108:111], v[80:95]
	ds_read_b128 v[6:9], v188
	s_waitcnt lgkmcnt(1)
	v_mfma_f32_32x32x16_bf16 v[80:95], v[2:5], v[112:115], v[80:95]
	ds_read_b128 v[2:5], v189
	s_waitcnt lgkmcnt(1)
	v_mfma_f32_32x32x16_bf16 v[80:95], v[6:9], v[116:119], v[80:95]
	ds_read_b128 v[6:9], v190
	s_waitcnt lgkmcnt(1)
	v_mfma_f32_32x32x16_bf16 v[80:95], v[2:5], v[120:123], v[80:95]
	s_waitcnt lgkmcnt(0)
	v_mfma_f32_32x32x16_bf16 v[80:95], v[6:9], v[124:127], v[80:95]
	s_and_saveexec_b64 s[10:11], vcc
	s_cbranch_execz .LBB0_283
	v_cmp_ne_u32_e32 vcc, 0, v162
	s_cmp_eq_u64 vcc, exec
	s_mov_b64 s[16:17], -1
	s_cbranch_scc0 .LBB0_282
	s_nop 5
	v_pk_mul_f32 v[2:3], v[80:81], s[96:97] op_sel_hi:[1,0]
	v_pk_mul_f32 v[4:5], v[82:83], s[96:97] op_sel_hi:[1,0]
	v_max3_f32 v1, v2, s89, v3
	v_max3_f32 v1, v1, v4, v5
	v_pk_mul_f32 v[6:7], v[84:85], s[96:97] op_sel_hi:[1,0]
	v_pk_mul_f32 v[8:9], v[86:87], s[96:97] op_sel_hi:[1,0]
	v_max3_f32 v1, v1, v6, v7
	v_max3_f32 v1, v1, v8, v9
	v_pk_mul_f32 v[10:11], v[88:89], s[96:97] op_sel_hi:[1,0]
	v_pk_mul_f32 v[12:13], v[90:91], s[96:97] op_sel_hi:[1,0]
	v_max3_f32 v1, v1, v10, v11
	v_max3_f32 v1, v1, v12, v13
	v_pk_mul_f32 v[14:15], v[92:93], s[96:97] op_sel_hi:[1,0]
	v_pk_mul_f32 v[160:161], v[94:95], s[96:97] op_sel_hi:[1,0]
	v_max3_f32 v1, v1, v14, v15
	v_max3_f32 v1, v1, v160, v161
	s_mov_b64 s[16:17], 0

; template <int MODE, int DQK>
; DEV void flash_half(FlashState& s, f32x16* imp, const bf16x8* qf, const char* st, int kh, int kb, int qpos, float cq,
;                     const float* __restrict__ cumk, bool selbit, float c2, float invl, int r32, int hh, int wqmin_, int wqmax_) {
;   f32x16 S = zero16();
;   const int pr32 = pi32(r32);
;   const char* kp = st + (kh * 32 + pr32) * (DQK * 2);
;   const int kkey = (DQK == 128) ? (pr32 & 15) : ((pr32 >> 1) & 7);
; #pragma unroll
;   for (int ks = 0; ks < DQK / 16; ++ks) { bf16x8 kf = *(const bf16x8*)(kp + (((ks * 2 + hh) ^ kkey) << 4)); S = mfma(kf, qf[ks], S); }
;   const int kbase = kb + 8 * hh;
;   float pr[16];
;   if (MODE == M_SB) {
;     float lk[16];
;     float Tlo = 0.f, Thi = 0.f;
; #pragma unroll
;     for (int r = 0; r < 16; ++r) {
;       int key = kbase + r + (r >= 8 ? 8 : 0);
;       float z2 = S[r] * c2;
;       float sp2 = fmaxf(z2, 0.f) + lg2(1.f + ex2(-fabsf(z2)));
;       lk[r] = (key < qpos) ? -sp2 : 0.f;
;       if (r < 8) Tlo += lk[r]; else Thi += lk[r];
;     }
;     float Plo = __shfl_xor(Tlo, 32), Phi = __shfl_xor(Thi, 32);
;     float baseLo = s.R + Thi + Phi + (hh == 0 ? Plo : 0.f);
;     float baseHi = s.R + (hh == 0 ? Phi : 0.f);
;     float run = 0.f;
; #pragma unroll
;     for (int r = 7; r >= 0; --r) { pr[r] = (kbase + r < qpos) ? ex2(S[r] * c2 + lk[r] + baseLo + run) : 0.f; run += lk[r]; }
;     run = 0.f;
; #pragma unroll
;     for (int r = 15; r >= 8; --r) { pr[r] = (kbase + r + 8 < qpos) ? ex2(S[r] * c2 + lk[r] + baseHi + run) : 0.f; run += lk[r]; }
;     s.R += Tlo + Thi + Plo + Phi;
;   } else {
;     float t[16];
;     float ck[16];
;     if (MODE == M_FOX) {
;       const float* cl = (const float*)(st + 32768) + kh * 32 + 8 * hh;
;       float4 a0 = *(const float4*)(cl), a1 = *(const float4*)(cl + 4);
;       float4 a2 = *(const float4*)(cl + 16), a3 = *(const float4*)(cl + 20);
;       ck[0] = a0.x; ck[1] = a0.y; ck[2] = a0.z; ck[3] = a0.w; ck[4] = a1.x; ck[5] = a1.y; ck[6] = a1.z; ck[7] = a1.w;
;       ck[8] = a2.x; ck[9] = a2.y; ck[10] = a2.z; ck[11] = a2.w; ck[12] = a3.x; ck[13] = a3.y; ck[14] = a3.z; ck[15] = a3.w;
;     }
;     float tmax = -__builtin_inff();
;     bool nomask = (kb + 31 <= wqmin_);
;     if (MODE == M_WIN) nomask = nomask && (kb > wqmax_ - 512);
;     if (MODE == M_SLC) nomask = nomask && __all(selbit);
.LBB0_334:
	s_lshl_b32 s10, s6, 6
	v_cmp_le_i32_e32 vcc, s10, v122
	s_and_saveexec_b64 s[24:25], vcc
	s_cbranch_execz .LBB0_350
	s_mul_i32 s11, s59, 0x8100
	v_add_u32_e32 v1, s11, v138
	v_add_u32_e32 v121, v1, v143
	ds_read_b128 v[2:5], v121
	v_add_u32_e32 v120, v1, v145
	ds_read_b128 v[6:9], v120
	v_add_u32_e32 v164, v1, v147
	v_add_u32_e32 v165, v1, v149
	s_or_b32 s6, s10, 31
	v_cmp_le_i32_e32 vcc, s6, v176
	s_waitcnt lgkmcnt(0)
	v_mfma_f32_32x32x16_bf16 v[80:95], v[2:5], v[108:111], 0
	ds_read_b128 v[2:5], v164
	v_mfma_f32_32x32x16_bf16 v[80:95], v[6:9], v[104:107], v[80:95]
	ds_read_b128 v[6:9], v165
	s_waitcnt lgkmcnt(1)
	v_mfma_f32_32x32x16_bf16 v[80:95], v[2:5], v[100:103], v[80:95]
	s_waitcnt lgkmcnt(0)
	v_mfma_f32_32x32x16_bf16 v[80:95], v[6:9], v[96:99], v[80:95]
	s_and_saveexec_b64 s[6:7], vcc
	s_xor_b64 s[6:7], exec, s[6:7]
	s_cbranch_execz .LBB0_337
	s_nop 8
	v_pk_mul_f32 v[2:3], v[80:81], s[88:89] op_sel_hi:[1,0]
	v_pk_mul_f32 v[4:5], v[82:83], s[88:89] op_sel_hi:[1,0]
	v_max3_f32 v1, v2, s89, v3
	v_max3_f32 v1, v1, v4, v5
	v_pk_mul_f32 v[6:7], v[84:85], s[88:89] op_sel_hi:[1,0]
	v_pk_mul_f32 v[8:9], v[86:87], s[88:89] op_sel_hi:[1,0]
	v_max3_f32 v1, v1, v6, v7
	v_max3_f32 v1, v1, v8, v9
	v_pk_mul_f32 v[10:11], v[88:89], s[88:89] op_sel_hi:[1,0]
	v_pk_mul_f32 v[12:13], v[90:91], s[88:89] op_sel_hi:[1,0]
	v_max3_f32 v1, v1, v10, v11
	v_max3_f32 v1, v1, v12, v13
	v_pk_mul_f32 v[14:15], v[92:93], s[88:89] op_sel_hi:[1,0]
	v_pk_mul_f32 v[118:119], v[94:95], s[88:89] op_sel_hi:[1,0]
	v_max3_f32 v1, v1, v14, v15
	v_max3_f32 v1, v1, v118, v119

; template <int MODE, int DQK>
; DEV void flash_half(FlashState& s, f32x16* imp, const bf16x8* qf, const char* st, int kh, int kb, int qpos, float cq,
;                     const float* __restrict__ cumk, bool selbit, float c2, float invl, int r32, int hh, int wqmin_, int wqmax_) {
;   f32x16 S = zero16();
;   const int pr32 = pi32(r32);
;   const char* kp = st + (kh * 32 + pr32) * (DQK * 2);
;   const int kkey = (DQK == 128) ? (pr32 & 15) : ((pr32 >> 1) & 7);
; #pragma unroll
;   for (int ks = 0; ks < DQK / 16; ++ks) { bf16x8 kf = *(const bf16x8*)(kp + (((ks * 2 + hh) ^ kkey) << 4)); S = mfma(kf, qf[ks], S); }
;   const int kbase = kb + 8 * hh;
;   float pr[16];
;   if (MODE == M_SB) {
;     float lk[16];
;     float Tlo = 0.f, Thi = 0.f;
; #pragma unroll
;     for (int r = 0; r < 16; ++r) {
;       int key = kbase + r + (r >= 8 ? 8 : 0);
;       float z2 = S[r] * c2;
;       float sp2 = fmaxf(z2, 0.f) + lg2(1.f + ex2(-fabsf(z2)));
;       lk[r] = (key < qpos) ? -sp2 : 0.f;
;       if (r < 8) Tlo += lk[r]; else Thi += lk[r];
;     }
;     float Plo = __shfl_xor(Tlo, 32), Phi = __shfl_xor(Thi, 32);
;     float baseLo = s.R + Thi + Phi + (hh == 0 ? Plo : 0.f);
;     float baseHi = s.R + (hh == 0 ? Phi : 0.f);
;     float run = 0.f;
; #pragma unroll
;     for (int r = 7; r >= 0; --r) { pr[r] = (kbase + r < qpos) ? ex2(S[r] * c2 + lk[r] + baseLo + run) : 0.f; run += lk[r]; }
;     run = 0.f;
; #pragma unroll
;     for (int r = 15; r >= 8; --r) { pr[r] = (kbase + r + 8 < qpos) ? ex2(S[r] * c2 + lk[r] + baseHi + run) : 0.f; run += lk[r]; }
;     s.R += Tlo + Thi + Plo + Phi;
;   } else {
;     float t[16];
;     float ck[16];
;     if (MODE == M_FOX) {
;       const float* cl = (const float*)(st + 32768) + kh * 32 + 8 * hh;
;       float4 a0 = *(const float4*)(cl), a1 = *(const float4*)(cl + 4);
;       float4 a2 = *(const float4*)(cl + 16), a3 = *(const float4*)(cl + 20);
;       ck[0] = a0.x; ck[1] = a0.y; ck[2] = a0.z; ck[3] = a0.w; ck[4] = a1.x; ck[5] = a1.y; ck[6] = a1.z; ck[7] = a1.w;
;       ck[8] = a2.x; ck[9] = a2.y; ck[10] = a2.z; ck[11] = a2.w; ck[12] = a3.x; ck[13] = a3.y; ck[14] = a3.z; ck[15] = a3.w;
;     }
;     float tmax = -__builtin_inff();
;     bool nomask = (kb + 31 <= wqmin_);
;     if (MODE == M_WIN) nomask = nomask && (kb > wqmax_ - 512);
;     if (MODE == M_SLC) nomask = nomask && __all(selbit);
.LBB0_358:
	s_lshl_b32 s10, s78, 6
	v_cmp_le_i32_e32 vcc, s10, v122
	s_and_saveexec_b64 s[78:79], vcc
	s_cbranch_execz .LBB0_374
	s_mul_i32 s11, s58, 0x8100
	v_add_u32_e32 v1, s11, v127
	v_add_u32_e32 v117, v1, v133
	ds_read_b128 v[2:5], v117
	v_add_u32_e32 v116, v1, v138
	ds_read_b128 v[6:9], v116
	v_add_u32_e32 v161, v1, v141
	v_add_u32_e32 v162, v1, v143
	s_or_b32 s6, s10, 31
	v_cmp_le_i32_e32 vcc, s6, v176
	s_waitcnt lgkmcnt(0)
	v_mfma_f32_32x32x16_bf16 v[80:95], v[2:5], v[96:99], 0
	ds_read_b128 v[2:5], v161
	v_mfma_f32_32x32x16_bf16 v[80:95], v[6:9], v[100:103], v[80:95]
	ds_read_b128 v[6:9], v162
	s_waitcnt lgkmcnt(1)
	v_mfma_f32_32x32x16_bf16 v[80:95], v[2:5], v[104:107], v[80:95]
	s_waitcnt lgkmcnt(0)
	v_mfma_f32_32x32x16_bf16 v[80:95], v[6:9], v[108:111], v[80:95]
	s_and_saveexec_b64 s[6:7], vcc
	s_xor_b64 s[6:7], exec, s[6:7]
	s_cbranch_execz .LBB0_361
	s_nop 8
	v_pk_mul_f32 v[2:3], v[80:81], s[88:89] op_sel_hi:[1,0]
	v_pk_mul_f32 v[4:5], v[82:83], s[88:89] op_sel_hi:[1,0]
	v_max3_f32 v1, v2, s89, v3
	v_max3_f32 v1, v1, v4, v5
	v_pk_mul_f32 v[6:7], v[84:85], s[88:89] op_sel_hi:[1,0]
	v_pk_mul_f32 v[8:9], v[86:87], s[88:89] op_sel_hi:[1,0]
	v_max3_f32 v1, v1, v6, v7
	v_max3_f32 v1, v1, v8, v9
	v_pk_mul_f32 v[10:11], v[88:89], s[88:89] op_sel_hi:[1,0]
	v_pk_mul_f32 v[12:13], v[90:91], s[88:89] op_sel_hi:[1,0]
	v_max3_f32 v1, v1, v10, v11
	v_max3_f32 v1, v1, v12, v13
	v_pk_mul_f32 v[14:15], v[92:93], s[88:89] op_sel_hi:[1,0]
	v_pk_mul_f32 v[114:115], v[94:95], s[88:89] op_sel_hi:[1,0]
	v_max3_f32 v1, v1, v14, v15
	v_max3_f32 v1, v1, v114, v115

; DEV int otid() { int t = threadIdx.x; asm volatile("" : "+v"(t)); return t; }
;   const int tid = otid(), lane = tid & 63, w = __builtin_amdgcn_readfirstlane(tid >> 6), wm = w >> 1, wn = w & 1, r32 = lane & 31, hh = lane >> 5;
;   f32x16 acc[MI / 2][2][2];
; #pragma unroll
;   for (int h = 0; h < MI / 2; ++h) { acc[h][0][0] = zero16(); acc[h][0][1] = zero16(); acc[h][1][0] = zero16(); acc[h][1][1] = zero16(); }
;   const int lrow = lane >> 2, lp = (lane & 3) ^ ((lane >> 4) & 3);
;   const bf16_t* ag = uni_ptr(A + (size_t)m0 * lda + kbeg);
;   const bf16_t* bg = uni_ptr(Bt + (size_t)n0 * ldb + kbeg);
;   const unsigned voffa = ((unsigned)lrow * (unsigned)lda + (unsigned)lp * 8u) * 2u;
;   const unsigned voffb = ((unsigned)lrow * (unsigned)ldb + (unsigned)lp * 8u) * 2u;
;   const int nk = (kend - kbeg) >> 5;
;   if (!pre) {
;     asm volatile("s_waitcnt vmcnt(0)" ::: "memory");
;     g2_issue<MI>(ag, bg, lda, ldb, voffa, voffb, lds, w);
;     if (nk > 1) g2_issue<MI>(ag + 32, bg + 32, lda, ldb, voffa, voffb, lds + G2_STAGE, w);
;   }
;   const int key = (r32 >> 2) & 3;
;   const int aoff = (wm * (MI * 32) + r32) * 64;
;   const int boff = 16384 + (wn * 64 + r32) * 64;
;   const int p0 = ((0 + hh) ^ key) * 16, p1 = ((2 + hh) ^ key) * 16;
;   const unsigned lbase = (unsigned)(size_t)lds;
;   const unsigned la0 = lbase + aoff + p0, la1 = lbase + aoff + p1, lb0 = lbase + boff + p0, lb1 = lbase + boff + p1;
;   int stg = 0;
.LBB0_536:
	s_xor_b64 s[12:13], s[2:3], -1
	v_writelane_b32 v239, s12, 34
	s_and_b32 s62, s14, 0xffffff80
	s_and_b32 s61, s14, 64
	v_writelane_b32 v239, s13, 35
	s_lshl_b64 s[16:17], s[4:5], 12
	s_lshl_b64 s[14:15], s[6:7], 12
	s_lshl_b64 s[12:13], s[8:9], 12
	s_lshl_b64 s[10:11], s[10:11], 12
	s_lshl_b64 s[8:9], s[18:19], 12
	s_lshl_b64 s[4:5], s[20:21], 12
	s_add_u32 s18, s59, 0x80
	s_addc_u32 s19, s63, 0
	s_add_u32 s6, s18, s4
	s_addc_u32 s7, s19, s5
	s_add_u32 s20, s18, s8
	s_addc_u32 s21, s19, s9
	s_add_u32 s18, s57, 0x80
	s_addc_u32 s19, s58, 0
	s_add_u32 s57, s18, s10
	s_addc_u32 s58, s19, s11
	v_and_b32_e32 v2, 63, v130
	s_add_u32 s59, s18, s12
	v_lshrrev_b32_e32 v133, 5, v2
	v_lshrrev_b32_e32 v2, 2, v130
	s_addc_u32 s63, s19, s13
	v_and_b32_e32 v152, 31, v130
	v_bfe_u32 v3, v130, 2, 2
	v_bitop3_b32 v2, v133, v2, 3 bitop3:0x78
	s_add_u32 s74, s18, s14
	v_or_b32_e32 v143, s61, v152
	v_lshlrev_b32_e32 v147, 4, v2
	v_bitop3_b32 v2, v133, v3, 2 bitop3:0x36
	s_addc_u32 s75, s19, s15
	v_or_b32_e32 v4, s62, v152
	v_lshlrev_b32_e32 v149, 6, v143
	v_lshlrev_b32_e32 v145, 4, v2
	s_add_u32 s76, s18, s16
	v_mov_b32_e32 v2, 0
	v_lshlrev_b32_e32 v138, 6, v4
	v_or_b32_e32 v141, 0x4000, v149
	s_addc_u32 s77, s19, s17
	s_mov_b32 s79, 0
	s_mov_b64 s[18:19], 0
	v_mov_b32_e32 v3, v2
	v_mov_b32_e32 v4, v2
	v_mov_b32_e32 v5, v2
	v_mov_b32_e32 v6, v2
	v_mov_b32_e32 v7, v2
	v_mov_b32_e32 v8, v2
	v_mov_b32_e32 v9, v2
	v_mov_b32_e32 v10, v2
	v_mov_b32_e32 v11, v2
	v_mov_b32_e32 v12, v2
	v_mov_b32_e32 v13, v2
	v_mov_b32_e32 v14, v2
	v_mov_b32_e32 v15, v2
	v_mov_b32_e32 v16, v2
	v_mov_b32_e32 v17, v2
	v_mov_b32_e32 v18, v2
	v_mov_b32_e32 v19, v2
	v_mov_b32_e32 v20, v2
	v_mov_b32_e32 v21, v2
	v_mov_b32_e32 v22, v2
	v_mov_b32_e32 v23, v2
	v_mov_b32_e32 v24, v2
	v_mov_b32_e32 v25, v2
	v_mov_b32_e32 v26, v2
	v_mov_b32_e32 v27, v2
	v_mov_b32_e32 v28, v2
	v_mov_b32_e32 v29, v2
	v_mov_b32_e32 v30, v2
	v_mov_b32_e32 v31, v2
	v_mov_b32_e32 v32, v2
	v_mov_b32_e32 v33, v2
	v_mov_b32_e32 v34, v2
	v_mov_b32_e32 v35, v2
	v_mov_b32_e32 v36, v2
	v_mov_b32_e32 v37, v2
	v_mov_b32_e32 v38, v2
	v_mov_b32_e32 v39, v2
	v_mov_b32_e32 v40, v2
	v_mov_b32_e32 v41, v2
	v_mov_b32_e32 v42, v2
	v_mov_b32_e32 v43, v2
	v_mov_b32_e32 v44, v2
	v_mov_b32_e32 v45, v2
	v_mov_b32_e32 v46, v2
	v_mov_b32_e32 v47, v2
	v_mov_b32_e32 v48, v2
	v_mov_b32_e32 v49, v2
	v_mov_b32_e32 v50, v2
	v_mov_b32_e32 v51, v2
	v_mov_b32_e32 v52, v2
	v_mov_b32_e32 v53, v2
	v_mov_b32_e32 v54, v2
	v_mov_b32_e32 v55, v2
	v_mov_b32_e32 v56, v2
	v_mov_b32_e32 v57, v2
	v_mov_b32_e32 v58, v2
	v_mov_b32_e32 v59, v2
	v_mov_b32_e32 v60, v2
	v_mov_b32_e32 v61, v2
	v_mov_b32_e32 v62, v2
	v_mov_b32_e32 v63, v2
	v_mov_b32_e32 v64, v2
	v_mov_b32_e32 v65, v2
	v_mov_b32_e32 v66, v2
	v_mov_b32_e32 v67, v2
	v_mov_b32_e32 v68, v2
	v_mov_b32_e32 v69, v2
	v_mov_b32_e32 v70, v2
	v_mov_b32_e32 v71, v2
	v_mov_b32_e32 v72, v2
	v_mov_b32_e32 v73, v2
	v_mov_b32_e32 v74, v2
	v_mov_b32_e32 v75, v2
	v_mov_b32_e32 v76, v2
	v_mov_b32_e32 v77, v2
	v_mov_b32_e32 v78, v2
	v_mov_b32_e32 v79, v2
	v_mov_b32_e32 v80, v2
	v_mov_b32_e32 v81, v2
	v_mov_b32_e32 v82, v2
	v_mov_b32_e32 v83, v2
	v_mov_b32_e32 v84, v2
	v_mov_b32_e32 v85, v2
	v_mov_b32_e32 v86, v2
	v_mov_b32_e32 v87, v2
	v_mov_b32_e32 v88, v2
	v_mov_b32_e32 v89, v2
	v_mov_b32_e32 v90, v2
	v_mov_b32_e32 v91, v2
	v_mov_b32_e32 v92, v2
	v_mov_b32_e32 v93, v2
	v_mov_b32_e32 v94, v2
	v_mov_b32_e32 v95, v2
	v_mov_b32_e32 v96, v2
	v_mov_b32_e32 v97, v2
	v_mov_b32_e32 v98, v2
	v_mov_b32_e32 v99, v2
	v_mov_b32_e32 v100, v2
	v_mov_b32_e32 v101, v2
	v_mov_b32_e32 v102, v2
	v_mov_b32_e32 v103, v2
	v_mov_b32_e32 v104, v2
	v_mov_b32_e32 v105, v2
	v_mov_b32_e32 v106, v2
	v_mov_b32_e32 v107, v2
	v_mov_b32_e32 v108, v2
	v_mov_b32_e32 v109, v2
	v_mov_b32_e32 v110, v2
	v_mov_b32_e32 v111, v2
	v_mov_b32_e32 v112, v2
	v_mov_b32_e32 v113, v2
	v_mov_b32_e32 v114, v2
	v_mov_b32_e32 v115, v2
	v_mov_b32_e32 v116, v2
	v_mov_b32_e32 v117, v2
	v_mov_b32_e32 v118, v2
	v_mov_b32_e32 v119, v2
	v_mov_b32_e32 v120, v2
	v_mov_b32_e32 v121, v2
	v_mov_b32_e32 v122, v2
	v_mov_b32_e32 v123, v2
	v_mov_b32_e32 v124, v2
	v_mov_b32_e32 v125, v2
	v_mov_b32_e32 v126, v2
	v_mov_b32_e32 v127, v2
	v_mov_b32_e32 v128, v2
	v_mov_b32_e32 v129, v2
	v_lshlrev_b32_e32 v191, 4, v200
.LBB0_537:
	s_cmp_gt_i32 s79, 0
	s_cselect_b32 s80, -1, 2
	s_add_i32 s80, s80, s79
	s_mul_i32 s82, s80, 0x6000
	s_add_u32 s80, s76, s18
	s_addc_u32 s81, s77, s19
	s_add_i32 s83, s1, s82
	s_cmp_eq_u32 s18, 0
	s_cbranch_scc1 .Lhyb_first_out
	s_waitcnt vmcnt(0)
	s_barrier
	s_add_i32 s98, s79, 1
	s_cmp_lg_u32 s79, 2
	s_cselect_b32 s98, s98, 0
	s_mul_i32 s98, s98, 0x6000
	s_add_i32 s99, s1, s98
	v_add_u32_e32 v238, s99, v191
	ds_write_b128 v238, v[214:217]
	s_add_i32 s99, s26, s98
	v_add_u32_e32 v190, s99, v191
	ds_write_b128 v190, v[218:221]
	s_add_i32 s99, s27, s98
	v_add_u32_e32 v238, s99, v191
	ds_write_b128 v238, v[222:225]
	s_add_i32 s99, s28, s98
	v_add_u32_e32 v190, s99, v191
	ds_write_b128 v190, v[226:229]
	s_add_i32 s99, s30, s98
	s_addk_i32 s99, 0x4000
	v_add_u32_e32 v238, s99, v191
	ds_write_b128 v238, v[230:233]
	s_add_i32 s99, s31, s98
	s_addk_i32 s99, 0x4000
	v_add_u32_e32 v190, s99, v191
	ds_write_b128 v190, v[234:237]
	s_branch .Lhyb_issue_out

; template <int MI>
; DEV void g2_issue(const bf16_t* __restrict__ abase, const bf16_t* __restrict__ bbase, size_t lda, size_t ldb, unsigned voffa, unsigned voffb,
;                   char* st, int w) {
;   const unsigned base = (unsigned)(size_t)st;
; #pragma unroll
;   for (int c = 0; c < MI; ++c) {
;     const int j = w * MI + c;
;     dma16s(abase + (size_t)(16 * j) * lda, voffa, __builtin_amdgcn_readfirstlane(base + j * 1024));
;   }
; #pragma unroll
;   for (int c = 0; c < 2; ++c) {
;     const int j = w * 2 + c;
;     dma16s(bbase + (size_t)(16 * j) * ldb, voffb, __builtin_amdgcn_readfirstlane(base + 16384 + j * 1024));
;   }
; }
.Lhyb_issue_out:
	s_cmpk_eq_i32 s18, 0xf80
	s_cbranch_scc1 .Lhyb_comp_out
	s_mov_b32 m0, s83
	s_nop 0
	global_load_lds_dwordx4 v1, s[80:81]
	global_load_dwordx4 v[214:217], v1, s[80:81] offset:64
	s_add_u32 s80, s74, s18
	s_addc_u32 s81, s75, s19
	s_add_i32 s83, s26, s82
	s_mov_b32 m0, s83
	s_nop 0
	global_load_lds_dwordx4 v1, s[80:81]
	global_load_dwordx4 v[218:221], v1, s[80:81] offset:64
	s_add_u32 s80, s59, s18
	s_addc_u32 s81, s63, s19
	s_add_i32 s83, s27, s82
	s_mov_b32 m0, s83
	s_nop 0
	global_load_lds_dwordx4 v1, s[80:81]
	global_load_dwordx4 v[222:225], v1, s[80:81] offset:64
	s_add_u32 s80, s57, s18
	s_addc_u32 s81, s58, s19
	s_add_i32 s83, s28, s82
	s_addk_i32 s82, 0x4000
	s_mov_b32 m0, s83
	s_nop 0
	global_load_lds_dwordx4 v1, s[80:81]
	global_load_dwordx4 v[226:229], v1, s[80:81] offset:64
	s_add_u32 s80, s20, s18
	s_addc_u32 s81, s21, s19
	s_add_i32 s83, s82, s30
	s_mov_b32 m0, s83
	s_nop 0
	global_load_lds_dwordx4 v1, s[80:81]
	global_load_dwordx4 v[230:233], v1, s[80:81] offset:64
	s_add_u32 s80, s6, s18
	s_addc_u32 s81, s7, s19
	s_add_i32 s82, s82, s31
	s_mov_b32 m0, s82
	s_nop 0
	global_load_lds_dwordx4 v1, s[80:81]
	global_load_dwordx4 v[234:237], v1, s[80:81] offset:64
;     ...
;     const unsigned so = (unsigned)(stg * G2_STAGE);
;     __builtin_amdgcn_s_setprio(1);
; #pragma unroll
;     for (int ks = 0; ks < 2; ++ks) {
;       const unsigned aa = (ks ? la1 : la0) + so, bb = (ks ? lb1 : lb0) + so;
;       bf16x8 fb0, fb1, fa0, fa1, fa2, fa3;
;       asm volatile("ds_read_b128 %0, %1" : "=v"(fb0) : "v"(bb));
;       asm volatile("ds_read_b128 %0, %1 offset:2048" : "=v"(fb1) : "v"(bb));
;       asm volatile("ds_read_b128 %0, %1" : "=v"(fa0) : "v"(aa));
;       asm volatile("ds_read_b128 %0, %1 offset:2048" : "=v"(fa1) : "v"(aa));
;       if constexpr (MI == 4) {
;         asm volatile("ds_read_b128 %0, %1 offset:4096" : "=v"(fa2) : "v"(aa));
;         asm volatile("ds_read_b128 %0, %1 offset:6144" : "=v"(fa3) : "v"(aa));
;         __builtin_amdgcn_sched_barrier(0);
;         asm volatile("s_waitcnt lgkmcnt(3)" : "+v"(fb0), "+v"(fb1), "+v"(fa0));
;         acc[0][0][0] = mfma(fa0, fb0, acc[0][0][0]); acc[0][0][1] = mfma(fa0, fb1, acc[0][0][1]); __builtin_amdgcn_sched_barrier(0);
;         asm volatile("s_waitcnt lgkmcnt(2)" : "+v"(fa1));
;         acc[0][1][0] = mfma(fa1, fb0, acc[0][1][0]); acc[0][1][1] = mfma(fa1, fb1, acc[0][1][1]); __builtin_amdgcn_sched_barrier(0);
;         asm volatile("s_waitcnt lgkmcnt(1)" : "+v"(fa2));
;         acc[MI / 2 - 1][0][0] = mfma(fa2, fb0, acc[MI / 2 - 1][0][0]); acc[MI / 2 - 1][0][1] = mfma(fa2, fb1, acc[MI / 2 - 1][0][1]); __builtin_amdgcn_sched_barrier(0);
;         asm volatile("s_waitcnt lgkmcnt(0)" : "+v"(fa3));
;         acc[MI / 2 - 1][1][0] = mfma(fa3, fb0, acc[MI / 2 - 1][1][0]); acc[MI / 2 - 1][1][1] = mfma(fa3, fb1, acc[MI / 2 - 1][1][1]); __builtin_amdgcn_sched_barrier(0);
;       } else {
;         __builtin_amdgcn_sched_barrier(0);
;         asm volatile("s_waitcnt lgkmcnt(1)" : "+v"(fb0), "+v"(fb1), "+v"(fa0));
;         acc[0][0][0] = mfma(fa0, fb0, acc[0][0][0]); acc[0][0][1] = mfma(fa0, fb1, acc[0][0][1]); __builtin_amdgcn_sched_barrier(0);
;         asm volatile("s_waitcnt lgkmcnt(0)" : "+v"(fa1));
;         acc[0][1][0] = mfma(fa1, fb0, acc[0][1][0]); acc[0][1][1] = mfma(fa1, fb1, acc[0][1][1]); __builtin_amdgcn_sched_barrier(0);
;       }
;     }
;     __builtin_amdgcn_s_setprio(0);
;     stg = stg == 2 ? 0 : stg + 1;
;   }
;   __syncthreads();
;   if (has_next) {
;     const bf16_t* agn = uni_ptr(A + (size_t)m0n * lda + kbeg);
.Lhyb_comp_out:
	s_mul_i32 s80, s79, 0x6000
	s_setprio 1
	v_add_u32_e32 v153, s80, v138
	v_add_u32_e32 v178, s80, v141
	v_add_u32_e32 v174, v153, v147
	v_add_u32_e32 v158, v178, v147
	ds_read_b128 v[154:157], v158
	ds_read_b128 v[158:161], v158 offset:2048
	ds_read_b128 v[162:165], v174
	ds_read_b128 v[166:169], v174 offset:2048
	ds_read_b128 v[170:173], v174 offset:4096
	ds_read_b128 v[174:177], v174 offset:6144
	s_nop 0
	s_waitcnt lgkmcnt(3)
	s_nop 0
	v_mfma_f32_32x32x16_bf16 v[114:129], v[162:165], v[154:157], v[114:129]
	v_mfma_f32_32x32x16_bf16 v[98:113], v[162:165], v[158:161], v[98:113]
	s_waitcnt lgkmcnt(2)
	s_nop 0
	v_mfma_f32_32x32x16_bf16 v[82:97], v[166:169], v[154:157], v[82:97]
	v_mfma_f32_32x32x16_bf16 v[66:81], v[166:169], v[158:161], v[66:81]
	s_waitcnt lgkmcnt(1)
	s_nop 0
	v_mfma_f32_32x32x16_bf16 v[50:65], v[170:173], v[154:157], v[50:65]
	v_mfma_f32_32x32x16_bf16 v[34:49], v[170:173], v[158:161], v[34:49]
	s_waitcnt lgkmcnt(0)
	s_nop 0
	v_mfma_f32_32x32x16_bf16 v[18:33], v[174:177], v[154:157], v[18:33]
	v_mfma_f32_32x32x16_bf16 v[2:17], v[174:177], v[158:161], v[2:17]
	v_add_u32_e32 v158, v178, v145
	v_add_u32_e32 v153, v153, v145
	ds_read_b128 v[154:157], v158
	ds_read_b128 v[158:161], v158 offset:2048
	ds_read_b128 v[162:165], v153
	ds_read_b128 v[166:169], v153 offset:2048
	ds_read_b128 v[170:173], v153 offset:4096
	ds_read_b128 v[174:177], v153 offset:6144
	s_nop 0
	s_waitcnt lgkmcnt(3)
	s_nop 0
	v_mfma_f32_32x32x16_bf16 v[114:129], v[162:165], v[154:157], v[114:129]
	v_mfma_f32_32x32x16_bf16 v[98:113], v[162:165], v[158:161], v[98:113]
	s_waitcnt lgkmcnt(2)
	s_nop 0
	v_mfma_f32_32x32x16_bf16 v[82:97], v[166:169], v[154:157], v[82:97]
	v_mfma_f32_32x32x16_bf16 v[66:81], v[166:169], v[158:161], v[66:81]
	s_waitcnt lgkmcnt(1)
	s_nop 0
	v_mfma_f32_32x32x16_bf16 v[50:65], v[170:173], v[154:157], v[50:65]
	v_mfma_f32_32x32x16_bf16 v[34:49], v[170:173], v[158:161], v[34:49]
	s_waitcnt lgkmcnt(0)
	s_nop 0
	v_mfma_f32_32x32x16_bf16 v[18:33], v[174:177], v[154:157], v[18:33]
	v_mfma_f32_32x32x16_bf16 v[2:17], v[174:177], v[158:161], v[2:17]
	s_setprio 0
	s_add_i32 s98, s79, 1
	s_cmp_lg_u32 s79, 2
	s_cselect_b32 s79, s98, 0
	s_waitcnt vmcnt(12)
	s_barrier
	s_mul_i32 s80, s79, 0x6000
	s_setprio 1
	v_add_u32_e32 v153, s80, v138
	v_add_u32_e32 v178, s80, v141
	v_add_u32_e32 v174, v153, v147
	v_add_u32_e32 v158, v178, v147
	ds_read_b128 v[154:157], v158
	ds_read_b128 v[158:161], v158 offset:2048
	ds_read_b128 v[162:165], v174
	ds_read_b128 v[166:169], v174 offset:2048
	ds_read_b128 v[170:173], v174 offset:4096
	ds_read_b128 v[174:177], v174 offset:6144
	s_nop 0
	s_waitcnt lgkmcnt(3)
	s_nop 0
	v_mfma_f32_32x32x16_bf16 v[114:129], v[162:165], v[154:157], v[114:129]
	v_mfma_f32_32x32x16_bf16 v[98:113], v[162:165], v[158:161], v[98:113]
	s_waitcnt lgkmcnt(2)
	s_nop 0
	v_mfma_f32_32x32x16_bf16 v[82:97], v[166:169], v[154:157], v[82:97]
	v_mfma_f32_32x32x16_bf16 v[66:81], v[166:169], v[158:161], v[66:81]
	s_waitcnt lgkmcnt(1)
	s_nop 0
	v_mfma_f32_32x32x16_bf16 v[50:65], v[170:173], v[154:157], v[50:65]
	v_mfma_f32_32x32x16_bf16 v[34:49], v[170:173], v[158:161], v[34:49]
	s_waitcnt lgkmcnt(0)
	s_nop 0
	v_mfma_f32_32x32x16_bf16 v[18:33], v[174:177], v[154:157], v[18:33]
	v_mfma_f32_32x32x16_bf16 v[2:17], v[174:177], v[158:161], v[2:17]
	v_add_u32_e32 v158, v178, v145
	v_add_u32_e32 v153, v153, v145
	ds_read_b128 v[154:157], v158
	ds_read_b128 v[158:161], v158 offset:2048
	ds_read_b128 v[162:165], v153
	ds_read_b128 v[166:169], v153 offset:2048
	ds_read_b128 v[170:173], v153 offset:4096
	ds_read_b128 v[174:177], v153 offset:6144
	s_nop 0
	s_waitcnt lgkmcnt(3)
	s_nop 0
	v_mfma_f32_32x32x16_bf16 v[114:129], v[162:165], v[154:157], v[114:129]
	v_mfma_f32_32x32x16_bf16 v[98:113], v[162:165], v[158:161], v[98:113]
	s_waitcnt lgkmcnt(2)
	s_nop 0
	v_mfma_f32_32x32x16_bf16 v[82:97], v[166:169], v[154:157], v[82:97]
	v_mfma_f32_32x32x16_bf16 v[66:81], v[166:169], v[158:161], v[66:81]
	s_waitcnt lgkmcnt(1)
	s_nop 0
	v_mfma_f32_32x32x16_bf16 v[50:65], v[170:173], v[154:157], v[50:65]
	v_mfma_f32_32x32x16_bf16 v[34:49], v[170:173], v[158:161], v[34:49]
	s_waitcnt lgkmcnt(0)
	s_nop 0
	v_mfma_f32_32x32x16_bf16 v[18:33], v[174:177], v[154:157], v[18:33]
	v_mfma_f32_32x32x16_bf16 v[2:17], v[174:177], v[158:161], v[2:17]
	s_add_i32 s98, s79, 1
	s_cmp_lg_u32 s79, 2
	s_cselect_b32 s79, s98, 0
	s_add_u32 s18, s18, 0x80
	s_addc_u32 s19, s19, 0
	s_cmpk_eq_i32 s18, 0x1000
	s_cbranch_scc0 .LBB0_537
	s_setprio 0
	s_and_b64 vcc, exec, s[2:3]
	s_waitcnt lgkmcnt(0)
	s_barrier
	s_cbranch_vccz .LBB0_540
	s_lshl_b32 s2, s53, 8
	s_ashr_i32 s3, s2, 31
	s_lshl_b32 s6, s54, 7
	s_lshl_b64 s[2:3], s[2:3], 12
	s_add_u32 s18, s24, s2
	s_addc_u32 s19, s25, s3
	s_ashr_i32 s7, s6, 31
	s_lshl_b64 s[2:3], s[6:7], 12
	s_add_u32 s20, s22, s2
	s_addc_u32 s21, s23, s3
	s_add_u32 s2, s18, s16
	s_addc_u32 s3, s19, s17
	s_add_u32 s6, s18, s14
	s_addc_u32 s7, s19, s15
	s_add_u32 s12, s18, s12
	s_addc_u32 s13, s19, s13
	s_add_u32 s10, s18, s10
	s_mov_b32 m0, s1
	s_nop 0
	global_load_lds_dwordx4 v1, s[2:3]
	s_addc_u32 s11, s19, s11
	s_mov_b32 m0, s26
	s_nop 0
	global_load_lds_dwordx4 v1, s[6:7]
	s_add_u32 s8, s20, s8
	s_mov_b32 m0, s27
	s_nop 0
	global_load_lds_dwordx4 v1, s[12:13]
	s_addc_u32 s9, s21, s9
	s_add_i32 s14, s30, 0x4000
	s_mov_b32 m0, s28
	s_nop 0
	global_load_lds_dwordx4 v1, s[10:11]
	s_add_u32 s4, s20, s4
	s_mov_b32 m0, s14
	s_nop 0
	global_load_lds_dwordx4 v1, s[8:9]
	s_addc_u32 s5, s21, s5
	s_add_i32 s14, s31, 0x4000
	s_add_u32 s2, s2, 64
	s_mov_b32 m0, s14
	s_nop 0
	global_load_lds_dwordx4 v1, s[4:5]
	s_addc_u32 s3, s3, 0
	s_addk_i32 s1, 0x6000
	s_mov_b32 m0, s1
	s_nop 0
	global_load_lds_dwordx4 v1, s[2:3]
	s_add_u32 s2, s6, 64
	s_addc_u32 s3, s7, 0
	s_add_i32 s1, s26, 0x6000
	s_mov_b32 m0, s1
	s_nop 0
	global_load_lds_dwordx4 v1, s[2:3]
	s_add_u32 s2, s12, 64
	s_addc_u32 s3, s13, 0
	s_add_i32 s1, s27, 0x6000
	s_mov_b32 m0, s1
	s_nop 0
	global_load_lds_dwordx4 v1, s[2:3]
	s_add_u32 s2, s10, 64
	s_addc_u32 s3, s11, 0
	s_add_i32 s1, s28, 0x6000
	s_mov_b32 m0, s1
	s_nop 0
	global_load_lds_dwordx4 v1, s[2:3]
	s_add_u32 s2, s8, 64
	s_addc_u32 s3, s9, 0
	s_add_i32 s1, s30, 0xa000
	s_mov_b32 m0, s1
	s_nop 0
	global_load_lds_dwordx4 v1, s[2:3]
	s_add_u32 s2, s4, 64
	s_addc_u32 s3, s5, 0
	s_add_i32 s1, s31, 0xa000
	s_mov_b32 m0, s1
	s_nop 0
	global_load_lds_dwordx4 v1, s[2:3]
